# peel first K-loop iteration of 5 GEMM loops: first-touch MFMAs take srcC=0, accumulator zeroing v_movs removed (on top of conv wait fix, noprio, rs7/rs1)
# speedup vs baseline: 1.0072x; 1.0072x over previous
.LBB0_96:
	s_add_u32 s40, s20, 0x100
	s_addc_u32 s41, s21, 0
	s_mov_b32 s42, -2
.Lk8a_peel:
	s_add_u32 s20, s18, 0x100
	s_addc_u32 s21, s19, 0
	s_add_i32 s43, 0, 0x10000
	s_cmp_eq_u32 s42, 40
	s_cselect_b32 s25, s15, s21
	s_cselect_b32 s24, s14, s20
	s_cselect_b32 s23, s17, s41
	s_cselect_b32 s22, s16, s40
	s_add_i32 s57, 0, 0x14000
	v_add_u32_e32 v136, s43, v183
	v_add_u32_e32 v170, s57, v183
	ds_read_b128 v[108:111], v136
	ds_read_b128 v[112:115], v136 offset:1024
	ds_read_b128 v[132:135], v136 offset:2048
	ds_read_b128 v[136:139], v136 offset:3072
	ds_read_b128 v[140:143], v170
	ds_read_b128 v[144:147], v170 offset:1024
	ds_read_b128 v[166:169], v170 offset:2048
	ds_read_b128 v[170:173], v170 offset:3072
	v_lshl_add_u64 v[194:195], s[18:19], 0, v[162:163]
	s_add_i32 m0, s28, 0xc000
	ds_read_b128 v[174:177], v184
	ds_read_b128 v[178:181], v184 offset:1024
	ds_read_b128 v[186:189], v184 offset:2048
	ds_read_b128 v[190:193], v184 offset:3072
	ds_read_b128 v[206:209], v184 offset:4096
	ds_read_b128 v[210:213], v184 offset:5120
	ds_read_b128 v[214:217], v184 offset:6144
	ds_read_b128 v[218:221], v184 offset:7168
	global_load_lds_dwordx4 v[194:195], off
	v_lshl_add_u64 v[194:195], s[18:19], 0, v[164:165]
	s_add_i32 m0, s28, 0xe000
	s_nop 0
	global_load_lds_dwordx4 v[194:195], off
	s_waitcnt vmcnt(8)
	s_waitcnt lgkmcnt(0)
	s_barrier
	s_waitcnt lgkmcnt(0)
	v_mfma_f32_16x16x32_bf16 v[152:155], v[108:111], v[174:177], 0
	v_mfma_f32_16x16x32_bf16 v[148:151], v[132:135], v[174:177], 0
	v_mfma_f32_16x16x32_bf16 v[128:131], v[108:111], v[186:189], 0
	v_mfma_f32_16x16x32_bf16 v[124:127], v[132:135], v[186:189], 0
	v_mfma_f32_16x16x32_bf16 v[100:103], v[108:111], v[206:209], 0
	v_mfma_f32_16x16x32_bf16 v[92:95], v[132:135], v[206:209], 0
	v_mfma_f32_16x16x32_bf16 v[80:83], v[108:111], v[214:217], 0
	v_mfma_f32_16x16x32_bf16 v[76:79], v[132:135], v[214:217], 0
	v_mfma_f32_16x16x32_bf16 v[152:155], v[112:115], v[178:181], v[152:155]
	v_mfma_f32_16x16x32_bf16 v[148:151], v[136:139], v[178:181], v[148:151]
	v_mfma_f32_16x16x32_bf16 v[128:131], v[112:115], v[190:193], v[128:131]
	v_mfma_f32_16x16x32_bf16 v[124:127], v[136:139], v[190:193], v[124:127]
	v_mfma_f32_16x16x32_bf16 v[100:103], v[112:115], v[210:213], v[100:103]
	v_mfma_f32_16x16x32_bf16 v[92:95], v[136:139], v[210:213], v[92:95]
	v_mfma_f32_16x16x32_bf16 v[80:83], v[112:115], v[218:221], v[80:83]
	v_mfma_f32_16x16x32_bf16 v[76:79], v[136:139], v[218:221], v[76:79]
	v_mfma_f32_16x16x32_bf16 v[104:107], v[140:143], v[174:177], 0
	v_mfma_f32_16x16x32_bf16 v[96:99], v[166:169], v[174:177], 0
	v_mfma_f32_16x16x32_bf16 v[120:123], v[140:143], v[186:189], 0
	v_mfma_f32_16x16x32_bf16 v[116:119], v[166:169], v[186:189], 0
	v_mfma_f32_16x16x32_bf16 v[88:91], v[140:143], v[206:209], 0
	v_mfma_f32_16x16x32_bf16 v[84:87], v[166:169], v[206:209], 0
	v_mfma_f32_16x16x32_bf16 v[72:75], v[140:143], v[214:217], 0
	v_mfma_f32_16x16x32_bf16 v[68:71], v[166:169], v[214:217], 0
	v_mfma_f32_16x16x32_bf16 v[104:107], v[144:147], v[178:181], v[104:107]
	v_mfma_f32_16x16x32_bf16 v[96:99], v[170:173], v[178:181], v[96:99]
	v_mfma_f32_16x16x32_bf16 v[120:123], v[144:147], v[190:193], v[120:123]
	v_mfma_f32_16x16x32_bf16 v[116:119], v[170:173], v[190:193], v[116:119]
	v_mfma_f32_16x16x32_bf16 v[88:91], v[144:147], v[210:213], v[88:91]
	v_mfma_f32_16x16x32_bf16 v[84:87], v[170:173], v[210:213], v[84:87]
	v_mfma_f32_16x16x32_bf16 v[72:75], v[144:147], v[218:221], v[72:75]
	v_mfma_f32_16x16x32_bf16 v[68:71], v[170:173], v[218:221], v[68:71]
	s_barrier
	s_add_i32 s18, s43, s27
	v_lshl_add_u64 v[194:195], s[22:23], 0, v[2:3]
	s_mov_b32 m0, s18
	ds_read_b128 v[174:177], v184 offset:16384
	ds_read_b128 v[178:181], v184 offset:17408
	ds_read_b128 v[186:189], v184 offset:18432
	ds_read_b128 v[190:193], v184 offset:19456
	ds_read_b128 v[206:209], v184 offset:20480
	ds_read_b128 v[210:213], v184 offset:21504
	ds_read_b128 v[214:217], v184 offset:22528
	ds_read_b128 v[218:221], v184 offset:23552
	global_load_lds_dwordx4 v[194:195], off
	s_add_i32 m0, s18, 0x2000
	s_add_u32 s18, s22, 0xb0000
	v_lshl_add_u64 v[236:237], s[22:23], 0, v[156:157]
	s_addc_u32 s19, s23, 0
	s_add_i32 s43, s57, s27
	global_load_lds_dwordx4 v[236:237], off
	v_lshl_add_u64 v[238:239], s[18:19], 0, v[2:3]
	s_mov_b32 m0, s43
	v_lshl_add_u64 v[240:241], s[24:25], 0, v[158:159]
	global_load_lds_dwordx4 v[238:239], off
	v_lshl_add_u64 v[238:239], s[18:19], 0, v[156:157]
	s_add_i32 m0, s43, 0x2000
	s_nop 0
	global_load_lds_dwordx4 v[238:239], off
	v_lshl_add_u64 v[238:239], s[24:25], 0, v[160:161]
	s_mov_b32 m0, s28
	s_nop 0
	global_load_lds_dwordx4 v[238:239], off
	s_mov_b32 m0, s29
	s_nop 0
	global_load_lds_dwordx4 v[240:241], off
	s_waitcnt vmcnt(8)
	s_waitcnt lgkmcnt(0)
	s_barrier
	s_waitcnt lgkmcnt(0)
	v_mfma_f32_16x16x32_bf16 v[64:67], v[108:111], v[174:177], 0
	v_mfma_f32_16x16x32_bf16 v[60:63], v[132:135], v[174:177], 0
	v_mfma_f32_16x16x32_bf16 v[48:51], v[108:111], v[186:189], 0
	v_mfma_f32_16x16x32_bf16 v[44:47], v[132:135], v[186:189], 0
	v_mfma_f32_16x16x32_bf16 v[32:35], v[108:111], v[206:209], 0
	v_mfma_f32_16x16x32_bf16 v[28:31], v[132:135], v[206:209], 0
	v_mfma_f32_16x16x32_bf16 v[16:19], v[108:111], v[214:217], 0
	v_mfma_f32_16x16x32_bf16 v[12:15], v[132:135], v[214:217], 0
	v_mfma_f32_16x16x32_bf16 v[64:67], v[112:115], v[178:181], v[64:67]
	v_mfma_f32_16x16x32_bf16 v[60:63], v[136:139], v[178:181], v[60:63]
	v_mfma_f32_16x16x32_bf16 v[48:51], v[112:115], v[190:193], v[48:51]
	v_mfma_f32_16x16x32_bf16 v[44:47], v[136:139], v[190:193], v[44:47]
	v_mfma_f32_16x16x32_bf16 v[32:35], v[112:115], v[210:213], v[32:35]
	v_mfma_f32_16x16x32_bf16 v[28:31], v[136:139], v[210:213], v[28:31]
	v_mfma_f32_16x16x32_bf16 v[16:19], v[112:115], v[218:221], v[16:19]
	v_mfma_f32_16x16x32_bf16 v[12:15], v[136:139], v[218:221], v[12:15]
	v_mfma_f32_16x16x32_bf16 v[56:59], v[140:143], v[174:177], 0
	v_mfma_f32_16x16x32_bf16 v[52:55], v[166:169], v[174:177], 0
	v_mfma_f32_16x16x32_bf16 v[40:43], v[140:143], v[186:189], 0
	v_mfma_f32_16x16x32_bf16 v[36:39], v[166:169], v[186:189], 0
	v_mfma_f32_16x16x32_bf16 v[24:27], v[140:143], v[206:209], 0
	v_mfma_f32_16x16x32_bf16 v[20:23], v[166:169], v[206:209], 0
	v_mfma_f32_16x16x32_bf16 v[8:11], v[140:143], v[214:217], 0
	v_mfma_f32_16x16x32_bf16 v[4:7], v[166:169], v[214:217], 0
	v_mfma_f32_16x16x32_bf16 v[56:59], v[144:147], v[178:181], v[56:59]
	v_mfma_f32_16x16x32_bf16 v[52:55], v[170:173], v[178:181], v[52:55]
	v_mfma_f32_16x16x32_bf16 v[40:43], v[144:147], v[190:193], v[40:43]
	v_mfma_f32_16x16x32_bf16 v[36:39], v[170:173], v[190:193], v[36:39]
	v_mfma_f32_16x16x32_bf16 v[24:27], v[144:147], v[210:213], v[24:27]
	v_mfma_f32_16x16x32_bf16 v[20:23], v[170:173], v[210:213], v[20:23]
	v_mfma_f32_16x16x32_bf16 v[8:11], v[144:147], v[218:221], v[8:11]
	v_mfma_f32_16x16x32_bf16 v[4:7], v[170:173], v[218:221], v[4:7]
	s_barrier
	s_add_i32 s43, 0, 0x18000
	s_add_i32 s57, 0, 0x1c000
	v_add_u32_e32 v136, s43, v183
	v_add_u32_e32 v170, s57, v183
	ds_read_b128 v[108:111], v136
	ds_read_b128 v[112:115], v136 offset:1024
	ds_read_b128 v[132:135], v136 offset:2048
	ds_read_b128 v[136:139], v136 offset:3072
	ds_read_b128 v[140:143], v170
	ds_read_b128 v[144:147], v170 offset:1024
	ds_read_b128 v[166:169], v170 offset:2048
	ds_read_b128 v[170:173], v170 offset:3072
	s_add_u32 s18, s24, 0xb0000
	s_addc_u32 s19, s25, 0
	s_mov_b32 m0, s30
	v_lshl_add_u64 v[242:243], s[18:19], 0, v[160:161]
	ds_read_b128 v[174:177], v184 offset:32768
	ds_read_b128 v[178:181], v184 offset:33792
	ds_read_b128 v[186:189], v184 offset:34816
	ds_read_b128 v[190:193], v184 offset:35840
	ds_read_b128 v[206:209], v184 offset:36864
	ds_read_b128 v[210:213], v184 offset:37888
	ds_read_b128 v[214:217], v184 offset:38912
	ds_read_b128 v[218:221], v184 offset:39936
	global_load_lds_dwordx4 v[242:243], off
	v_lshl_add_u64 v[242:243], s[18:19], 0, v[158:159]
	s_mov_b32 m0, s31
	s_nop 0
	global_load_lds_dwordx4 v[242:243], off
	s_waitcnt vmcnt(8)
	s_waitcnt lgkmcnt(0)
	s_barrier
	s_waitcnt lgkmcnt(0)
	v_mfma_f32_16x16x32_bf16 v[152:155], v[108:111], v[174:177], v[152:155]
	v_mfma_f32_16x16x32_bf16 v[148:151], v[132:135], v[174:177], v[148:151]
	v_mfma_f32_16x16x32_bf16 v[128:131], v[108:111], v[186:189], v[128:131]
	v_mfma_f32_16x16x32_bf16 v[124:127], v[132:135], v[186:189], v[124:127]
	v_mfma_f32_16x16x32_bf16 v[100:103], v[108:111], v[206:209], v[100:103]
	v_mfma_f32_16x16x32_bf16 v[92:95], v[132:135], v[206:209], v[92:95]
	v_mfma_f32_16x16x32_bf16 v[80:83], v[108:111], v[214:217], v[80:83]
	v_mfma_f32_16x16x32_bf16 v[76:79], v[132:135], v[214:217], v[76:79]
	v_mfma_f32_16x16x32_bf16 v[152:155], v[112:115], v[178:181], v[152:155]
	v_mfma_f32_16x16x32_bf16 v[148:151], v[136:139], v[178:181], v[148:151]
	v_mfma_f32_16x16x32_bf16 v[128:131], v[112:115], v[190:193], v[128:131]
	v_mfma_f32_16x16x32_bf16 v[124:127], v[136:139], v[190:193], v[124:127]
	v_mfma_f32_16x16x32_bf16 v[100:103], v[112:115], v[210:213], v[100:103]
	v_mfma_f32_16x16x32_bf16 v[92:95], v[136:139], v[210:213], v[92:95]
	v_mfma_f32_16x16x32_bf16 v[80:83], v[112:115], v[218:221], v[80:83]
	v_mfma_f32_16x16x32_bf16 v[76:79], v[136:139], v[218:221], v[76:79]
	v_mfma_f32_16x16x32_bf16 v[104:107], v[140:143], v[174:177], v[104:107]
	v_mfma_f32_16x16x32_bf16 v[96:99], v[166:169], v[174:177], v[96:99]
	v_mfma_f32_16x16x32_bf16 v[120:123], v[140:143], v[186:189], v[120:123]
	v_mfma_f32_16x16x32_bf16 v[116:119], v[166:169], v[186:189], v[116:119]
	v_mfma_f32_16x16x32_bf16 v[88:91], v[140:143], v[206:209], v[88:91]
	v_mfma_f32_16x16x32_bf16 v[84:87], v[166:169], v[206:209], v[84:87]
	v_mfma_f32_16x16x32_bf16 v[72:75], v[140:143], v[214:217], v[72:75]
	v_mfma_f32_16x16x32_bf16 v[68:71], v[166:169], v[214:217], v[68:71]
	v_mfma_f32_16x16x32_bf16 v[104:107], v[144:147], v[178:181], v[104:107]
	v_mfma_f32_16x16x32_bf16 v[96:99], v[170:173], v[178:181], v[96:99]
	v_mfma_f32_16x16x32_bf16 v[120:123], v[144:147], v[190:193], v[120:123]
	v_mfma_f32_16x16x32_bf16 v[116:119], v[170:173], v[190:193], v[116:119]
	v_mfma_f32_16x16x32_bf16 v[88:91], v[144:147], v[210:213], v[88:91]
	v_mfma_f32_16x16x32_bf16 v[84:87], v[170:173], v[210:213], v[84:87]
	v_mfma_f32_16x16x32_bf16 v[72:75], v[144:147], v[218:221], v[72:75]
	v_mfma_f32_16x16x32_bf16 v[68:71], v[170:173], v[218:221], v[68:71]
	s_barrier
	s_add_i32 s18, s43, s27
	v_lshl_add_u64 v[194:195], v[194:195], 0, s[96:97]
	s_mov_b32 m0, s18
	ds_read_b128 v[174:177], v184 offset:49152
	ds_read_b128 v[178:181], v184 offset:50176
	ds_read_b128 v[186:189], v184 offset:51200
	ds_read_b128 v[190:193], v184 offset:52224
	ds_read_b128 v[206:209], v184 offset:53248
	ds_read_b128 v[210:213], v184 offset:54272
	ds_read_b128 v[214:217], v184 offset:55296
	ds_read_b128 v[218:221], v184 offset:56320
	global_load_lds_dwordx4 v[194:195], off
	s_add_i32 m0, s18, 0x2000
	s_add_u32 s18, s22, 0xb0080
	v_lshl_add_u64 v[194:195], v[236:237], 0, s[96:97]
	s_addc_u32 s19, s23, 0
	s_add_i32 s22, s57, s27
	global_load_lds_dwordx4 v[194:195], off
	v_lshl_add_u64 v[194:195], s[18:19], 0, v[2:3]
	s_mov_b32 m0, s22
	s_nop 0
	global_load_lds_dwordx4 v[194:195], off
	v_lshl_add_u64 v[194:195], s[18:19], 0, v[156:157]
	s_add_i32 m0, s22, 0x2000
	s_nop 0
	global_load_lds_dwordx4 v[194:195], off
	v_lshl_add_u64 v[194:195], v[238:239], 0, s[96:97]
	s_mov_b32 m0, s36
	s_nop 0
	global_load_lds_dwordx4 v[194:195], off
	v_lshl_add_u64 v[194:195], v[240:241], 0, s[96:97]
	s_mov_b32 m0, s37
	s_nop 0
	global_load_lds_dwordx4 v[194:195], off
	s_waitcnt vmcnt(8)
	s_waitcnt lgkmcnt(0)
	s_barrier
	s_waitcnt lgkmcnt(0)
	v_mfma_f32_16x16x32_bf16 v[64:67], v[108:111], v[174:177], v[64:67]
	v_mfma_f32_16x16x32_bf16 v[60:63], v[132:135], v[174:177], v[60:63]
	v_mfma_f32_16x16x32_bf16 v[48:51], v[108:111], v[186:189], v[48:51]
	v_mfma_f32_16x16x32_bf16 v[44:47], v[132:135], v[186:189], v[44:47]
	v_mfma_f32_16x16x32_bf16 v[32:35], v[108:111], v[206:209], v[32:35]
	v_mfma_f32_16x16x32_bf16 v[28:31], v[132:135], v[206:209], v[28:31]
	v_mfma_f32_16x16x32_bf16 v[16:19], v[108:111], v[214:217], v[16:19]
	v_mfma_f32_16x16x32_bf16 v[12:15], v[132:135], v[214:217], v[12:15]
	v_mfma_f32_16x16x32_bf16 v[64:67], v[112:115], v[178:181], v[64:67]
	v_mfma_f32_16x16x32_bf16 v[60:63], v[136:139], v[178:181], v[60:63]
	v_mfma_f32_16x16x32_bf16 v[48:51], v[112:115], v[190:193], v[48:51]
	v_mfma_f32_16x16x32_bf16 v[44:47], v[136:139], v[190:193], v[44:47]
	v_mfma_f32_16x16x32_bf16 v[32:35], v[112:115], v[210:213], v[32:35]
	v_mfma_f32_16x16x32_bf16 v[28:31], v[136:139], v[210:213], v[28:31]
	v_mfma_f32_16x16x32_bf16 v[16:19], v[112:115], v[218:221], v[16:19]
	v_mfma_f32_16x16x32_bf16 v[12:15], v[136:139], v[218:221], v[12:15]
	v_mfma_f32_16x16x32_bf16 v[56:59], v[140:143], v[174:177], v[56:59]
	v_mfma_f32_16x16x32_bf16 v[52:55], v[166:169], v[174:177], v[52:55]
	v_mfma_f32_16x16x32_bf16 v[40:43], v[140:143], v[186:189], v[40:43]
	v_mfma_f32_16x16x32_bf16 v[36:39], v[166:169], v[186:189], v[36:39]
	v_mfma_f32_16x16x32_bf16 v[24:27], v[140:143], v[206:209], v[24:27]
	v_mfma_f32_16x16x32_bf16 v[20:23], v[166:169], v[206:209], v[20:23]
	v_mfma_f32_16x16x32_bf16 v[8:11], v[140:143], v[214:217], v[8:11]
	v_mfma_f32_16x16x32_bf16 v[4:7], v[166:169], v[214:217], v[4:7]
	v_mfma_f32_16x16x32_bf16 v[56:59], v[144:147], v[178:181], v[56:59]
	v_mfma_f32_16x16x32_bf16 v[52:55], v[170:173], v[178:181], v[52:55]
	v_mfma_f32_16x16x32_bf16 v[40:43], v[144:147], v[190:193], v[40:43]
	v_mfma_f32_16x16x32_bf16 v[36:39], v[170:173], v[190:193], v[36:39]
	v_mfma_f32_16x16x32_bf16 v[24:27], v[144:147], v[210:213], v[24:27]
	v_mfma_f32_16x16x32_bf16 v[20:23], v[170:173], v[210:213], v[20:23]
	v_mfma_f32_16x16x32_bf16 v[8:11], v[144:147], v[218:221], v[8:11]
	v_mfma_f32_16x16x32_bf16 v[4:7], v[170:173], v[218:221], v[4:7]
	s_barrier
	s_add_i32 s42, s42, 2
	s_add_u32 s40, s40, 0x100
	s_addc_u32 s41, s41, 0
	s_cmp_gt_u32 s42, 41
	s_mov_b64 s[18:19], s[20:21]

.LBB0_155:
	s_add_u32 s66, s16, 0x100
	s_addc_u32 s67, s17, 0
	s_mov_b32 s68, -2
.Lk8b_peel:
	s_add_u32 s16, s14, 0x100
	s_addc_u32 s17, s15, 0
	s_add_i32 s69, 0, 0x10000
	s_cmp_eq_u32 s68, 40
	s_cselect_b32 s21, s41, s17
	s_cselect_b32 s20, s40, s16
	v_add_u32_e32 v2, s69, v207
	s_cselect_b32 s19, s57, s67
	s_cselect_b32 s18, s56, s66
	s_add_i32 s70, 0, 0x14000
	ds_read_b128 v[108:111], v2
	ds_read_b128 v[112:115], v2 offset:1024
	ds_read_b128 v[132:135], v2 offset:2048
	ds_read_b128 v[136:139], v2 offset:3072
	v_add_u32_e32 v2, s70, v207
	ds_read_b128 v[148:151], v2
	ds_read_b128 v[152:155], v2 offset:1024
	ds_read_b128 v[168:171], v2 offset:2048
	ds_read_b128 v[172:175], v2 offset:3072
	v_lshl_add_u64 v[236:237], s[14:15], 0, v[164:165]
	s_add_i32 m0, s25, 0xc000
	ds_read_b128 v[176:179], v208
	ds_read_b128 v[180:183], v208 offset:1024
	ds_read_b128 v[184:187], v208 offset:2048
	ds_read_b128 v[188:191], v208 offset:3072
	ds_read_b128 v[192:195], v208 offset:4096
	ds_read_b128 v[210:213], v208 offset:5120
	ds_read_b128 v[214:217], v208 offset:6144
	ds_read_b128 v[218:221], v208 offset:7168
	global_load_lds_dwordx4 v[236:237], off
	v_lshl_add_u64 v[236:237], s[14:15], 0, v[166:167]
	s_add_i32 m0, s25, 0xe000
	s_nop 0
	global_load_lds_dwordx4 v[236:237], off
	s_waitcnt vmcnt(8)
	s_waitcnt lgkmcnt(0)
	s_barrier
	s_waitcnt lgkmcnt(0)
	v_mfma_f32_16x16x32_bf16 v[144:147], v[108:111], v[176:179], 0
	v_mfma_f32_16x16x32_bf16 v[140:143], v[132:135], v[176:179], 0
	v_mfma_f32_16x16x32_bf16 v[128:131], v[108:111], v[184:187], 0
	v_mfma_f32_16x16x32_bf16 v[124:127], v[132:135], v[184:187], 0
	v_mfma_f32_16x16x32_bf16 v[96:99], v[108:111], v[192:195], 0
	v_mfma_f32_16x16x32_bf16 v[92:95], v[132:135], v[192:195], 0
	v_mfma_f32_16x16x32_bf16 v[80:83], v[108:111], v[214:217], 0
	v_mfma_f32_16x16x32_bf16 v[76:79], v[132:135], v[214:217], 0
	v_mfma_f32_16x16x32_bf16 v[144:147], v[112:115], v[180:183], v[144:147]
	v_mfma_f32_16x16x32_bf16 v[140:143], v[136:139], v[180:183], v[140:143]
	v_mfma_f32_16x16x32_bf16 v[128:131], v[112:115], v[188:191], v[128:131]
	v_mfma_f32_16x16x32_bf16 v[124:127], v[136:139], v[188:191], v[124:127]
	v_mfma_f32_16x16x32_bf16 v[96:99], v[112:115], v[210:213], v[96:99]
	v_mfma_f32_16x16x32_bf16 v[92:95], v[136:139], v[210:213], v[92:95]
	v_mfma_f32_16x16x32_bf16 v[80:83], v[112:115], v[218:221], v[80:83]
	v_mfma_f32_16x16x32_bf16 v[76:79], v[136:139], v[218:221], v[76:79]
	v_mfma_f32_16x16x32_bf16 v[104:107], v[148:151], v[176:179], 0
	v_mfma_f32_16x16x32_bf16 v[100:103], v[168:171], v[176:179], 0
	v_mfma_f32_16x16x32_bf16 v[120:123], v[148:151], v[184:187], 0
	v_mfma_f32_16x16x32_bf16 v[116:119], v[168:171], v[184:187], 0
	v_mfma_f32_16x16x32_bf16 v[88:91], v[148:151], v[192:195], 0
	v_mfma_f32_16x16x32_bf16 v[84:87], v[168:171], v[192:195], 0
	v_mfma_f32_16x16x32_bf16 v[72:75], v[148:151], v[214:217], 0
	v_mfma_f32_16x16x32_bf16 v[68:71], v[168:171], v[214:217], 0
	v_mfma_f32_16x16x32_bf16 v[104:107], v[152:155], v[180:183], v[104:107]
	v_mfma_f32_16x16x32_bf16 v[100:103], v[172:175], v[180:183], v[100:103]
	v_mfma_f32_16x16x32_bf16 v[120:123], v[152:155], v[188:191], v[120:123]
	v_mfma_f32_16x16x32_bf16 v[116:119], v[172:175], v[188:191], v[116:119]
	v_mfma_f32_16x16x32_bf16 v[88:91], v[152:155], v[210:213], v[88:91]
	v_mfma_f32_16x16x32_bf16 v[84:87], v[172:175], v[210:213], v[84:87]
	v_mfma_f32_16x16x32_bf16 v[72:75], v[152:155], v[218:221], v[72:75]
	v_mfma_f32_16x16x32_bf16 v[68:71], v[172:175], v[218:221], v[68:71]
	s_barrier
	s_add_i32 s14, s69, s24
	v_lshl_add_u64 v[236:237], s[18:19], 0, v[160:161]
	s_mov_b32 m0, s14
	ds_read_b128 v[176:179], v208 offset:16384
	ds_read_b128 v[180:183], v208 offset:17408
	ds_read_b128 v[184:187], v208 offset:18432
	ds_read_b128 v[188:191], v208 offset:19456
	ds_read_b128 v[192:195], v208 offset:20480
	ds_read_b128 v[210:213], v208 offset:21504
	ds_read_b128 v[214:217], v208 offset:22528
	ds_read_b128 v[218:221], v208 offset:23552
	global_load_lds_dwordx4 v[236:237], off
	s_add_i32 m0, s14, 0x2000
	s_add_u32 s14, s18, 0xb0000
	v_lshl_add_u64 v[238:239], s[18:19], 0, v[156:157]
	s_addc_u32 s15, s19, 0
	s_add_i32 s69, s70, s24
	global_load_lds_dwordx4 v[238:239], off
	v_lshl_add_u64 v[240:241], s[14:15], 0, v[160:161]
	s_mov_b32 m0, s69
	v_lshl_add_u64 v[242:243], s[20:21], 0, v[158:159]
	global_load_lds_dwordx4 v[240:241], off
	v_lshl_add_u64 v[240:241], s[14:15], 0, v[156:157]
	s_add_i32 m0, s69, 0x2000
	s_nop 0
	global_load_lds_dwordx4 v[240:241], off
	v_lshl_add_u64 v[240:241], s[20:21], 0, v[162:163]
	s_mov_b32 m0, s25
	s_nop 0
	global_load_lds_dwordx4 v[240:241], off
	s_mov_b32 m0, s26
	s_nop 0
	global_load_lds_dwordx4 v[242:243], off
	s_waitcnt vmcnt(8)
	s_waitcnt lgkmcnt(0)
	s_barrier
	s_waitcnt lgkmcnt(0)
	v_mfma_f32_16x16x32_bf16 v[64:67], v[108:111], v[176:179], 0
	v_mfma_f32_16x16x32_bf16 v[60:63], v[132:135], v[176:179], 0
	v_mfma_f32_16x16x32_bf16 v[48:51], v[108:111], v[184:187], 0
	v_mfma_f32_16x16x32_bf16 v[44:47], v[132:135], v[184:187], 0
	v_mfma_f32_16x16x32_bf16 v[32:35], v[108:111], v[192:195], 0
	v_mfma_f32_16x16x32_bf16 v[28:31], v[132:135], v[192:195], 0
	v_mfma_f32_16x16x32_bf16 v[16:19], v[108:111], v[214:217], 0
	v_mfma_f32_16x16x32_bf16 v[12:15], v[132:135], v[214:217], 0
	v_mfma_f32_16x16x32_bf16 v[64:67], v[112:115], v[180:183], v[64:67]
	v_mfma_f32_16x16x32_bf16 v[60:63], v[136:139], v[180:183], v[60:63]
	v_mfma_f32_16x16x32_bf16 v[48:51], v[112:115], v[188:191], v[48:51]
	v_mfma_f32_16x16x32_bf16 v[44:47], v[136:139], v[188:191], v[44:47]
	v_mfma_f32_16x16x32_bf16 v[32:35], v[112:115], v[210:213], v[32:35]
	v_mfma_f32_16x16x32_bf16 v[28:31], v[136:139], v[210:213], v[28:31]
	v_mfma_f32_16x16x32_bf16 v[16:19], v[112:115], v[218:221], v[16:19]
	v_mfma_f32_16x16x32_bf16 v[12:15], v[136:139], v[218:221], v[12:15]
	v_mfma_f32_16x16x32_bf16 v[56:59], v[148:151], v[176:179], 0
	v_mfma_f32_16x16x32_bf16 v[52:55], v[168:171], v[176:179], 0
	v_mfma_f32_16x16x32_bf16 v[40:43], v[148:151], v[184:187], 0
	v_mfma_f32_16x16x32_bf16 v[36:39], v[168:171], v[184:187], 0
	v_mfma_f32_16x16x32_bf16 v[24:27], v[148:151], v[192:195], 0
	v_mfma_f32_16x16x32_bf16 v[20:23], v[168:171], v[192:195], 0
	v_mfma_f32_16x16x32_bf16 v[8:11], v[148:151], v[214:217], 0
	v_mfma_f32_16x16x32_bf16 v[4:7], v[168:171], v[214:217], 0
	v_mfma_f32_16x16x32_bf16 v[56:59], v[152:155], v[180:183], v[56:59]
	v_mfma_f32_16x16x32_bf16 v[52:55], v[172:175], v[180:183], v[52:55]
	v_mfma_f32_16x16x32_bf16 v[40:43], v[152:155], v[188:191], v[40:43]
	v_mfma_f32_16x16x32_bf16 v[36:39], v[172:175], v[188:191], v[36:39]
	v_mfma_f32_16x16x32_bf16 v[24:27], v[152:155], v[210:213], v[24:27]
	v_mfma_f32_16x16x32_bf16 v[20:23], v[172:175], v[210:213], v[20:23]
	v_mfma_f32_16x16x32_bf16 v[8:11], v[152:155], v[218:221], v[8:11]
	v_mfma_f32_16x16x32_bf16 v[4:7], v[172:175], v[218:221], v[4:7]
	s_barrier
	s_add_i32 s69, 0, 0x18000
	v_add_u32_e32 v2, s69, v207
	s_add_i32 s70, 0, 0x1c000
	ds_read_b128 v[108:111], v2
	ds_read_b128 v[112:115], v2 offset:1024
	ds_read_b128 v[132:135], v2 offset:2048
	ds_read_b128 v[136:139], v2 offset:3072
	v_add_u32_e32 v2, s70, v207
	ds_read_b128 v[148:151], v2
	ds_read_b128 v[152:155], v2 offset:1024
	ds_read_b128 v[168:171], v2 offset:2048
	ds_read_b128 v[172:175], v2 offset:3072
	s_add_u32 s14, s20, 0xb0000
	s_addc_u32 s15, s21, 0
	s_mov_b32 m0, s27
	v_lshl_add_u64 v[244:245], s[14:15], 0, v[162:163]
	ds_read_b128 v[176:179], v208 offset:32768
	ds_read_b128 v[180:183], v208 offset:33792
	ds_read_b128 v[184:187], v208 offset:34816
	ds_read_b128 v[188:191], v208 offset:35840
	ds_read_b128 v[192:195], v208 offset:36864
	ds_read_b128 v[210:213], v208 offset:37888
	ds_read_b128 v[214:217], v208 offset:38912
	ds_read_b128 v[218:221], v208 offset:39936
	global_load_lds_dwordx4 v[244:245], off
	v_lshl_add_u64 v[244:245], s[14:15], 0, v[158:159]
	s_mov_b32 m0, s28
	s_nop 0
	global_load_lds_dwordx4 v[244:245], off
	s_waitcnt vmcnt(8)
	s_waitcnt lgkmcnt(0)
	s_barrier
	s_waitcnt lgkmcnt(0)
	v_mfma_f32_16x16x32_bf16 v[144:147], v[108:111], v[176:179], v[144:147]
	v_mfma_f32_16x16x32_bf16 v[140:143], v[132:135], v[176:179], v[140:143]
	v_mfma_f32_16x16x32_bf16 v[128:131], v[108:111], v[184:187], v[128:131]
	v_mfma_f32_16x16x32_bf16 v[124:127], v[132:135], v[184:187], v[124:127]
	v_mfma_f32_16x16x32_bf16 v[96:99], v[108:111], v[192:195], v[96:99]
	v_mfma_f32_16x16x32_bf16 v[92:95], v[132:135], v[192:195], v[92:95]
	v_mfma_f32_16x16x32_bf16 v[80:83], v[108:111], v[214:217], v[80:83]
	v_mfma_f32_16x16x32_bf16 v[76:79], v[132:135], v[214:217], v[76:79]
	v_mfma_f32_16x16x32_bf16 v[144:147], v[112:115], v[180:183], v[144:147]
	v_mfma_f32_16x16x32_bf16 v[140:143], v[136:139], v[180:183], v[140:143]
	v_mfma_f32_16x16x32_bf16 v[128:131], v[112:115], v[188:191], v[128:131]
	v_mfma_f32_16x16x32_bf16 v[124:127], v[136:139], v[188:191], v[124:127]
	v_mfma_f32_16x16x32_bf16 v[96:99], v[112:115], v[210:213], v[96:99]
	v_mfma_f32_16x16x32_bf16 v[92:95], v[136:139], v[210:213], v[92:95]
	v_mfma_f32_16x16x32_bf16 v[80:83], v[112:115], v[218:221], v[80:83]
	v_mfma_f32_16x16x32_bf16 v[76:79], v[136:139], v[218:221], v[76:79]
	v_mfma_f32_16x16x32_bf16 v[104:107], v[148:151], v[176:179], v[104:107]
	v_mfma_f32_16x16x32_bf16 v[100:103], v[168:171], v[176:179], v[100:103]
	v_mfma_f32_16x16x32_bf16 v[120:123], v[148:151], v[184:187], v[120:123]
	v_mfma_f32_16x16x32_bf16 v[116:119], v[168:171], v[184:187], v[116:119]
	v_mfma_f32_16x16x32_bf16 v[88:91], v[148:151], v[192:195], v[88:91]
	v_mfma_f32_16x16x32_bf16 v[84:87], v[168:171], v[192:195], v[84:87]
	v_mfma_f32_16x16x32_bf16 v[72:75], v[148:151], v[214:217], v[72:75]
	v_mfma_f32_16x16x32_bf16 v[68:71], v[168:171], v[214:217], v[68:71]
	v_mfma_f32_16x16x32_bf16 v[104:107], v[152:155], v[180:183], v[104:107]
	v_mfma_f32_16x16x32_bf16 v[100:103], v[172:175], v[180:183], v[100:103]
	v_mfma_f32_16x16x32_bf16 v[120:123], v[152:155], v[188:191], v[120:123]
	v_mfma_f32_16x16x32_bf16 v[116:119], v[172:175], v[188:191], v[116:119]
	v_mfma_f32_16x16x32_bf16 v[88:91], v[152:155], v[210:213], v[88:91]
	v_mfma_f32_16x16x32_bf16 v[84:87], v[172:175], v[210:213], v[84:87]
	v_mfma_f32_16x16x32_bf16 v[72:75], v[152:155], v[218:221], v[72:75]
	v_mfma_f32_16x16x32_bf16 v[68:71], v[172:175], v[218:221], v[68:71]
	s_barrier
	s_add_i32 s14, s69, s24
	v_lshl_add_u64 v[236:237], v[236:237], 0, s[96:97]
	s_mov_b32 m0, s14
	ds_read_b128 v[176:179], v208 offset:49152
	ds_read_b128 v[180:183], v208 offset:50176
	ds_read_b128 v[184:187], v208 offset:51200
	ds_read_b128 v[188:191], v208 offset:52224
	ds_read_b128 v[192:195], v208 offset:53248
	ds_read_b128 v[210:213], v208 offset:54272
	ds_read_b128 v[214:217], v208 offset:55296
	ds_read_b128 v[218:221], v208 offset:56320
	global_load_lds_dwordx4 v[236:237], off
	s_add_i32 m0, s14, 0x2000
	s_add_u32 s14, s18, 0xb0080
	v_lshl_add_u64 v[236:237], v[238:239], 0, s[96:97]
	s_addc_u32 s15, s19, 0
	s_add_i32 s18, s70, s24
	global_load_lds_dwordx4 v[236:237], off
	v_lshl_add_u64 v[236:237], s[14:15], 0, v[160:161]
	s_mov_b32 m0, s18
	s_nop 0
	global_load_lds_dwordx4 v[236:237], off
	v_lshl_add_u64 v[236:237], s[14:15], 0, v[156:157]
	s_add_i32 m0, s18, 0x2000
	s_nop 0
	global_load_lds_dwordx4 v[236:237], off
	v_lshl_add_u64 v[236:237], v[240:241], 0, s[96:97]
	s_mov_b32 m0, s31
	s_nop 0
	global_load_lds_dwordx4 v[236:237], off
	v_lshl_add_u64 v[236:237], v[242:243], 0, s[96:97]
	s_mov_b32 m0, s34
	s_nop 0
	global_load_lds_dwordx4 v[236:237], off
	s_waitcnt vmcnt(8)
	s_waitcnt lgkmcnt(0)
	s_barrier
	s_waitcnt lgkmcnt(0)
	v_mfma_f32_16x16x32_bf16 v[64:67], v[108:111], v[176:179], v[64:67]
	v_mfma_f32_16x16x32_bf16 v[60:63], v[132:135], v[176:179], v[60:63]
	v_mfma_f32_16x16x32_bf16 v[48:51], v[108:111], v[184:187], v[48:51]
	v_mfma_f32_16x16x32_bf16 v[44:47], v[132:135], v[184:187], v[44:47]
	v_mfma_f32_16x16x32_bf16 v[32:35], v[108:111], v[192:195], v[32:35]
	v_mfma_f32_16x16x32_bf16 v[28:31], v[132:135], v[192:195], v[28:31]
	v_mfma_f32_16x16x32_bf16 v[16:19], v[108:111], v[214:217], v[16:19]
	v_mfma_f32_16x16x32_bf16 v[12:15], v[132:135], v[214:217], v[12:15]
	v_mfma_f32_16x16x32_bf16 v[64:67], v[112:115], v[180:183], v[64:67]
	v_mfma_f32_16x16x32_bf16 v[60:63], v[136:139], v[180:183], v[60:63]
	v_mfma_f32_16x16x32_bf16 v[48:51], v[112:115], v[188:191], v[48:51]
	v_mfma_f32_16x16x32_bf16 v[44:47], v[136:139], v[188:191], v[44:47]
	v_mfma_f32_16x16x32_bf16 v[32:35], v[112:115], v[210:213], v[32:35]
	v_mfma_f32_16x16x32_bf16 v[28:31], v[136:139], v[210:213], v[28:31]
	v_mfma_f32_16x16x32_bf16 v[16:19], v[112:115], v[218:221], v[16:19]
	v_mfma_f32_16x16x32_bf16 v[12:15], v[136:139], v[218:221], v[12:15]
	v_mfma_f32_16x16x32_bf16 v[56:59], v[148:151], v[176:179], v[56:59]
	v_mfma_f32_16x16x32_bf16 v[52:55], v[168:171], v[176:179], v[52:55]
	v_mfma_f32_16x16x32_bf16 v[40:43], v[148:151], v[184:187], v[40:43]
	v_mfma_f32_16x16x32_bf16 v[36:39], v[168:171], v[184:187], v[36:39]
	v_mfma_f32_16x16x32_bf16 v[24:27], v[148:151], v[192:195], v[24:27]
	v_mfma_f32_16x16x32_bf16 v[20:23], v[168:171], v[192:195], v[20:23]
	v_mfma_f32_16x16x32_bf16 v[8:11], v[148:151], v[214:217], v[8:11]
	v_mfma_f32_16x16x32_bf16 v[4:7], v[168:171], v[214:217], v[4:7]
	v_mfma_f32_16x16x32_bf16 v[56:59], v[152:155], v[180:183], v[56:59]
	v_mfma_f32_16x16x32_bf16 v[52:55], v[172:175], v[180:183], v[52:55]
	v_mfma_f32_16x16x32_bf16 v[40:43], v[152:155], v[188:191], v[40:43]
	v_mfma_f32_16x16x32_bf16 v[36:39], v[172:175], v[188:191], v[36:39]
	v_mfma_f32_16x16x32_bf16 v[24:27], v[152:155], v[210:213], v[24:27]
	v_mfma_f32_16x16x32_bf16 v[20:23], v[172:175], v[210:213], v[20:23]
	v_mfma_f32_16x16x32_bf16 v[8:11], v[152:155], v[218:221], v[8:11]
	v_mfma_f32_16x16x32_bf16 v[4:7], v[172:175], v[218:221], v[4:7]
	s_barrier
	s_add_i32 s68, s68, 2
	s_add_u32 s66, s66, 0x100
	s_addc_u32 s67, s67, 0
	s_cmp_gt_u32 s68, 41
	s_mov_b64 s[14:15], s[16:17]

.LBB0_315:
	v_lshlrev_b32_e32 v142, 4, v0
	s_lshl_b32 s100, s57, 14
	s_add_u32 s100, s18, s100
	s_addc_u32 s101, s19, 0
	v_readfirstlane_b32 s25, v142
	s_nop 3
	s_add_i32 m0, s25, 0x20400
	s_nop 0
	global_load_lds_dwordx4 v142, s[100:101]
	v_add_u32_e32 v142, 0x2000, v142
	s_add_i32 m0, s25, 0x22400
	s_nop 0
	global_load_lds_dwordx4 v142, s[100:101]
	s_ashr_i32 s25, s24, 31
	s_lshl_b64 s[26:27], s[24:25], 19
	s_add_u32 s26, s37, s26
	s_addc_u32 s27, s44, s27
	s_and_b64 s[34:35], s[38:39], exec
	s_cselect_b32 s25, s27, s29
	s_cselect_b32 s58, s26, s28
	s_ashr_i32 s23, s22, 31
	s_lshl_b64 s[34:35], s[22:23], 19
	s_add_u32 s42, s40, s34
	s_addc_u32 s43, s41, s35
	s_and_b64 s[34:35], s[38:39], exec
	s_cselect_b32 s23, s43, s31
	s_cselect_b32 s59, s42, s30
	s_add_u32 s28, s28, 0x40080
	s_addc_u32 s29, s29, 0
	s_add_u32 s60, s30, 0x100
	s_addc_u32 s61, s31, 0
	s_mov_b32 s62, -2
.Lk7_peel:
	s_add_u32 s30, s28, 0xfffc0080
	s_addc_u32 s31, s29, -1
	s_add_i32 s63, 0, 0x10000
	s_cmp_eq_u32 s62, 12
	s_cselect_b32 s35, s25, s31
	s_cselect_b32 s34, s58, s30
	v_add_u32_e32 v142, s63, v145
	s_cselect_b32 s31, s23, s61
	s_cselect_b32 s30, s59, s60
	s_add_i32 s66, 0, 0x14000
	ds_read_b128 v[148:151], v142
	ds_read_b128 v[152:155], v142 offset:1024
	ds_read_b128 v[156:159], v142 offset:2048
	ds_read_b128 v[160:163], v142 offset:3072
	v_add_u32_e32 v142, s66, v145
	ds_read_b128 v[164:167], v142
	ds_read_b128 v[168:171], v142 offset:1024
	ds_read_b128 v[172:175], v142 offset:2048
	ds_read_b128 v[176:179], v142 offset:3072
	v_lshl_add_u64 v[142:143], s[28:29], 0, v[138:139]
	s_add_i32 m0, s45, 0xc000
	ds_read_b128 v[180:183], v146
	ds_read_b128 v[184:187], v146 offset:1024
	ds_read_b128 v[188:191], v146 offset:2048
	ds_read_b128 v[192:195], v146 offset:3072
	ds_read_b128 v[206:209], v146 offset:4096
	ds_read_b128 v[210:213], v146 offset:5120
	ds_read_b128 v[214:217], v146 offset:6144
	ds_read_b128 v[218:221], v146 offset:7168
	global_load_lds_dwordx4 v[142:143], off
	v_lshl_add_u64 v[142:143], s[28:29], 0, v[140:141]
	s_add_i32 m0, s45, 0xe000
	s_nop 0
	global_load_lds_dwordx4 v[142:143], off
	s_waitcnt vmcnt(8)
	s_waitcnt lgkmcnt(0)
	s_barrier
	s_waitcnt lgkmcnt(0)
	v_mfma_f32_16x16x32_bf16 v[128:131], v[148:151], v[180:183], 0
	v_mfma_f32_16x16x32_bf16 v[120:123], v[156:159], v[180:183], 0
	v_mfma_f32_16x16x32_bf16 v[112:115], v[148:151], v[188:191], 0
	v_mfma_f32_16x16x32_bf16 v[104:107], v[156:159], v[188:191], 0
	v_mfma_f32_16x16x32_bf16 v[96:99], v[148:151], v[206:209], 0
	v_mfma_f32_16x16x32_bf16 v[88:91], v[156:159], v[206:209], 0
	v_mfma_f32_16x16x32_bf16 v[80:83], v[148:151], v[214:217], 0
	v_mfma_f32_16x16x32_bf16 v[72:75], v[156:159], v[214:217], 0
	v_mfma_f32_16x16x32_bf16 v[128:131], v[152:155], v[184:187], v[128:131]
	v_mfma_f32_16x16x32_bf16 v[120:123], v[160:163], v[184:187], v[120:123]
	v_mfma_f32_16x16x32_bf16 v[112:115], v[152:155], v[192:195], v[112:115]
	v_mfma_f32_16x16x32_bf16 v[104:107], v[160:163], v[192:195], v[104:107]
	v_mfma_f32_16x16x32_bf16 v[96:99], v[152:155], v[210:213], v[96:99]
	v_mfma_f32_16x16x32_bf16 v[88:91], v[160:163], v[210:213], v[88:91]
	v_mfma_f32_16x16x32_bf16 v[80:83], v[152:155], v[218:221], v[80:83]
	v_mfma_f32_16x16x32_bf16 v[72:75], v[160:163], v[218:221], v[72:75]
	v_mfma_f32_16x16x32_bf16 v[124:127], v[164:167], v[180:183], 0
	v_mfma_f32_16x16x32_bf16 v[116:119], v[172:175], v[180:183], 0
	v_mfma_f32_16x16x32_bf16 v[108:111], v[164:167], v[188:191], 0
	v_mfma_f32_16x16x32_bf16 v[100:103], v[172:175], v[188:191], 0
	v_mfma_f32_16x16x32_bf16 v[92:95], v[164:167], v[206:209], 0
	v_mfma_f32_16x16x32_bf16 v[84:87], v[172:175], v[206:209], 0
	v_mfma_f32_16x16x32_bf16 v[76:79], v[164:167], v[214:217], 0
	v_mfma_f32_16x16x32_bf16 v[68:71], v[172:175], v[214:217], 0
	v_mfma_f32_16x16x32_bf16 v[124:127], v[168:171], v[184:187], v[124:127]
	v_mfma_f32_16x16x32_bf16 v[116:119], v[176:179], v[184:187], v[116:119]
	v_mfma_f32_16x16x32_bf16 v[108:111], v[168:171], v[192:195], v[108:111]
	v_mfma_f32_16x16x32_bf16 v[100:103], v[176:179], v[192:195], v[100:103]
	v_mfma_f32_16x16x32_bf16 v[92:95], v[168:171], v[210:213], v[92:95]
	v_mfma_f32_16x16x32_bf16 v[84:87], v[176:179], v[210:213], v[84:87]
	v_mfma_f32_16x16x32_bf16 v[76:79], v[168:171], v[218:221], v[76:79]
	v_mfma_f32_16x16x32_bf16 v[68:71], v[176:179], v[218:221], v[68:71]
	s_barrier
	s_add_i32 s63, s63, s36
	v_lshl_add_u64 v[142:143], s[30:31], 0, v[2:3]
	s_mov_b32 m0, s63
	ds_read_b128 v[180:183], v146 offset:16384
	ds_read_b128 v[184:187], v146 offset:17408
	ds_read_b128 v[188:191], v146 offset:18432
	ds_read_b128 v[192:195], v146 offset:19456
	ds_read_b128 v[206:209], v146 offset:20480
	ds_read_b128 v[210:213], v146 offset:21504
	ds_read_b128 v[214:217], v146 offset:22528
	ds_read_b128 v[218:221], v146 offset:23552
	global_load_lds_dwordx4 v[142:143], off
	s_add_i32 m0, s63, 0x2000
	s_add_u32 s64, s30, 0x40000
	v_lshl_add_u64 v[236:237], s[30:31], 0, v[132:133]
	s_addc_u32 s65, s31, 0
	s_add_i32 s63, s66, s36
	global_load_lds_dwordx4 v[236:237], off
	v_lshl_add_u64 v[238:239], s[64:65], 0, v[2:3]
	s_mov_b32 m0, s63
	v_lshl_add_u64 v[240:241], s[34:35], 0, v[134:135]
	global_load_lds_dwordx4 v[238:239], off
	v_lshl_add_u64 v[238:239], s[64:65], 0, v[132:133]
	s_add_i32 m0, s63, 0x2000
	s_nop 0
	global_load_lds_dwordx4 v[238:239], off
	v_lshl_add_u64 v[238:239], s[34:35], 0, v[136:137]
	s_mov_b32 m0, s45
	s_nop 0
	global_load_lds_dwordx4 v[238:239], off
	s_mov_b32 m0, s46
	s_nop 0
	global_load_lds_dwordx4 v[240:241], off
	s_waitcnt vmcnt(8)
	s_waitcnt lgkmcnt(0)
	s_barrier
	s_waitcnt lgkmcnt(0)
	v_mfma_f32_16x16x32_bf16 v[64:67], v[148:151], v[180:183], 0
	v_mfma_f32_16x16x32_bf16 v[56:59], v[156:159], v[180:183], 0
	v_mfma_f32_16x16x32_bf16 v[48:51], v[148:151], v[188:191], 0
	v_mfma_f32_16x16x32_bf16 v[40:43], v[156:159], v[188:191], 0
	v_mfma_f32_16x16x32_bf16 v[32:35], v[148:151], v[206:209], 0
	v_mfma_f32_16x16x32_bf16 v[24:27], v[156:159], v[206:209], 0
	v_mfma_f32_16x16x32_bf16 v[16:19], v[148:151], v[214:217], 0
	v_mfma_f32_16x16x32_bf16 v[8:11], v[156:159], v[214:217], 0
	v_mfma_f32_16x16x32_bf16 v[64:67], v[152:155], v[184:187], v[64:67]
	v_mfma_f32_16x16x32_bf16 v[56:59], v[160:163], v[184:187], v[56:59]
	v_mfma_f32_16x16x32_bf16 v[48:51], v[152:155], v[192:195], v[48:51]
	v_mfma_f32_16x16x32_bf16 v[40:43], v[160:163], v[192:195], v[40:43]
	v_mfma_f32_16x16x32_bf16 v[32:35], v[152:155], v[210:213], v[32:35]
	v_mfma_f32_16x16x32_bf16 v[24:27], v[160:163], v[210:213], v[24:27]
	v_mfma_f32_16x16x32_bf16 v[16:19], v[152:155], v[218:221], v[16:19]
	v_mfma_f32_16x16x32_bf16 v[8:11], v[160:163], v[218:221], v[8:11]
	v_mfma_f32_16x16x32_bf16 v[60:63], v[164:167], v[180:183], 0
	v_mfma_f32_16x16x32_bf16 v[52:55], v[172:175], v[180:183], 0
	v_mfma_f32_16x16x32_bf16 v[44:47], v[164:167], v[188:191], 0
	v_mfma_f32_16x16x32_bf16 v[36:39], v[172:175], v[188:191], 0
	v_mfma_f32_16x16x32_bf16 v[28:31], v[164:167], v[206:209], 0
	v_mfma_f32_16x16x32_bf16 v[20:23], v[172:175], v[206:209], 0
	v_mfma_f32_16x16x32_bf16 v[12:15], v[164:167], v[214:217], 0
	v_mfma_f32_16x16x32_bf16 v[4:7], v[172:175], v[214:217], 0
	v_mfma_f32_16x16x32_bf16 v[60:63], v[168:171], v[184:187], v[60:63]
	v_mfma_f32_16x16x32_bf16 v[52:55], v[176:179], v[184:187], v[52:55]
	v_mfma_f32_16x16x32_bf16 v[44:47], v[168:171], v[192:195], v[44:47]
	v_mfma_f32_16x16x32_bf16 v[36:39], v[176:179], v[192:195], v[36:39]
	v_mfma_f32_16x16x32_bf16 v[28:31], v[168:171], v[210:213], v[28:31]
	v_mfma_f32_16x16x32_bf16 v[20:23], v[176:179], v[210:213], v[20:23]
	v_mfma_f32_16x16x32_bf16 v[12:15], v[168:171], v[218:221], v[12:15]
	v_mfma_f32_16x16x32_bf16 v[4:7], v[176:179], v[218:221], v[4:7]
	s_barrier
	s_add_i32 s63, 0, 0x18000
	v_add_u32_e32 v147, s63, v145
	s_add_i32 s64, 0, 0x1c000
	ds_read_b128 v[148:151], v147
	ds_read_b128 v[152:155], v147 offset:1024
	ds_read_b128 v[156:159], v147 offset:2048
	ds_read_b128 v[160:163], v147 offset:3072
	v_add_u32_e32 v147, s64, v145
	ds_read_b128 v[164:167], v147
	ds_read_b128 v[168:171], v147 offset:1024
	ds_read_b128 v[172:175], v147 offset:2048
	ds_read_b128 v[176:179], v147 offset:3072
	s_add_u32 s34, s34, 0x40000
	s_addc_u32 s35, s35, 0
	s_mov_b32 m0, s47
	v_lshl_add_u64 v[242:243], s[34:35], 0, v[136:137]
	ds_read_b128 v[180:183], v146 offset:32768
	ds_read_b128 v[184:187], v146 offset:33792
	ds_read_b128 v[188:191], v146 offset:34816
	ds_read_b128 v[192:195], v146 offset:35840
	ds_read_b128 v[206:209], v146 offset:36864
	ds_read_b128 v[210:213], v146 offset:37888
	ds_read_b128 v[214:217], v146 offset:38912
	ds_read_b128 v[218:221], v146 offset:39936
	global_load_lds_dwordx4 v[242:243], off
	v_lshl_add_u64 v[242:243], s[34:35], 0, v[134:135]
	s_mov_b32 m0, s48
	s_nop 0
	global_load_lds_dwordx4 v[242:243], off
	s_waitcnt vmcnt(8)
	s_waitcnt lgkmcnt(0)
	s_barrier
	s_waitcnt lgkmcnt(0)
	v_mfma_f32_16x16x32_bf16 v[128:131], v[148:151], v[180:183], v[128:131]
	v_mfma_f32_16x16x32_bf16 v[120:123], v[156:159], v[180:183], v[120:123]
	v_mfma_f32_16x16x32_bf16 v[112:115], v[148:151], v[188:191], v[112:115]
	v_mfma_f32_16x16x32_bf16 v[104:107], v[156:159], v[188:191], v[104:107]
	v_mfma_f32_16x16x32_bf16 v[96:99], v[148:151], v[206:209], v[96:99]
	v_mfma_f32_16x16x32_bf16 v[88:91], v[156:159], v[206:209], v[88:91]
	v_mfma_f32_16x16x32_bf16 v[80:83], v[148:151], v[214:217], v[80:83]
	v_mfma_f32_16x16x32_bf16 v[72:75], v[156:159], v[214:217], v[72:75]
	v_mfma_f32_16x16x32_bf16 v[128:131], v[152:155], v[184:187], v[128:131]
	v_mfma_f32_16x16x32_bf16 v[120:123], v[160:163], v[184:187], v[120:123]
	v_mfma_f32_16x16x32_bf16 v[112:115], v[152:155], v[192:195], v[112:115]
	v_mfma_f32_16x16x32_bf16 v[104:107], v[160:163], v[192:195], v[104:107]
	v_mfma_f32_16x16x32_bf16 v[96:99], v[152:155], v[210:213], v[96:99]
	v_mfma_f32_16x16x32_bf16 v[88:91], v[160:163], v[210:213], v[88:91]
	v_mfma_f32_16x16x32_bf16 v[80:83], v[152:155], v[218:221], v[80:83]
	v_mfma_f32_16x16x32_bf16 v[72:75], v[160:163], v[218:221], v[72:75]
	v_mfma_f32_16x16x32_bf16 v[124:127], v[164:167], v[180:183], v[124:127]
	v_mfma_f32_16x16x32_bf16 v[116:119], v[172:175], v[180:183], v[116:119]
	v_mfma_f32_16x16x32_bf16 v[108:111], v[164:167], v[188:191], v[108:111]
	v_mfma_f32_16x16x32_bf16 v[100:103], v[172:175], v[188:191], v[100:103]
	v_mfma_f32_16x16x32_bf16 v[92:95], v[164:167], v[206:209], v[92:95]
	v_mfma_f32_16x16x32_bf16 v[84:87], v[172:175], v[206:209], v[84:87]
	v_mfma_f32_16x16x32_bf16 v[76:79], v[164:167], v[214:217], v[76:79]
	v_mfma_f32_16x16x32_bf16 v[68:71], v[172:175], v[214:217], v[68:71]
	v_mfma_f32_16x16x32_bf16 v[124:127], v[168:171], v[184:187], v[124:127]
	v_mfma_f32_16x16x32_bf16 v[116:119], v[176:179], v[184:187], v[116:119]
	v_mfma_f32_16x16x32_bf16 v[108:111], v[168:171], v[192:195], v[108:111]
	v_mfma_f32_16x16x32_bf16 v[100:103], v[176:179], v[192:195], v[100:103]
	v_mfma_f32_16x16x32_bf16 v[92:95], v[168:171], v[210:213], v[92:95]
	v_mfma_f32_16x16x32_bf16 v[84:87], v[176:179], v[210:213], v[84:87]
	v_mfma_f32_16x16x32_bf16 v[76:79], v[168:171], v[218:221], v[76:79]
	v_mfma_f32_16x16x32_bf16 v[68:71], v[176:179], v[218:221], v[68:71]
	s_barrier
	s_add_i32 s34, s63, s36
	v_lshl_add_u64 v[142:143], v[142:143], 0, s[96:97]
	s_mov_b32 m0, s34
	ds_read_b128 v[180:183], v146 offset:49152
	ds_read_b128 v[184:187], v146 offset:50176
	ds_read_b128 v[188:191], v146 offset:51200
	ds_read_b128 v[192:195], v146 offset:52224
	ds_read_b128 v[206:209], v146 offset:53248
	ds_read_b128 v[210:213], v146 offset:54272
	ds_read_b128 v[214:217], v146 offset:55296
	ds_read_b128 v[218:221], v146 offset:56320
	global_load_lds_dwordx4 v[142:143], off
	s_add_i32 m0, s34, 0x2000
	s_add_u32 s30, s30, 0x40080
	v_lshl_add_u64 v[142:143], v[236:237], 0, s[96:97]
	s_addc_u32 s31, s31, 0
	s_add_i32 s34, s64, s36
	global_load_lds_dwordx4 v[142:143], off
	v_lshl_add_u64 v[142:143], s[30:31], 0, v[2:3]
	s_mov_b32 m0, s34
	s_nop 0
	global_load_lds_dwordx4 v[142:143], off
	v_lshl_add_u64 v[142:143], s[30:31], 0, v[132:133]
	s_add_i32 m0, s34, 0x2000
	s_nop 0
	global_load_lds_dwordx4 v[142:143], off
	v_lshl_add_u64 v[142:143], v[238:239], 0, s[96:97]
	s_mov_b32 m0, s51
	s_nop 0
	global_load_lds_dwordx4 v[142:143], off
	v_lshl_add_u64 v[142:143], v[240:241], 0, s[96:97]
	s_mov_b32 m0, s52
	s_nop 0
	global_load_lds_dwordx4 v[142:143], off
	s_waitcnt vmcnt(8)
	s_waitcnt lgkmcnt(0)
	s_barrier
	s_waitcnt lgkmcnt(0)
	v_mfma_f32_16x16x32_bf16 v[64:67], v[148:151], v[180:183], v[64:67]
	v_mfma_f32_16x16x32_bf16 v[56:59], v[156:159], v[180:183], v[56:59]
	v_mfma_f32_16x16x32_bf16 v[48:51], v[148:151], v[188:191], v[48:51]
	v_mfma_f32_16x16x32_bf16 v[40:43], v[156:159], v[188:191], v[40:43]
	v_mfma_f32_16x16x32_bf16 v[32:35], v[148:151], v[206:209], v[32:35]
	v_mfma_f32_16x16x32_bf16 v[24:27], v[156:159], v[206:209], v[24:27]
	v_mfma_f32_16x16x32_bf16 v[16:19], v[148:151], v[214:217], v[16:19]
	v_mfma_f32_16x16x32_bf16 v[8:11], v[156:159], v[214:217], v[8:11]
	v_mfma_f32_16x16x32_bf16 v[64:67], v[152:155], v[184:187], v[64:67]
	v_mfma_f32_16x16x32_bf16 v[56:59], v[160:163], v[184:187], v[56:59]
	v_mfma_f32_16x16x32_bf16 v[48:51], v[152:155], v[192:195], v[48:51]
	v_mfma_f32_16x16x32_bf16 v[40:43], v[160:163], v[192:195], v[40:43]
	v_mfma_f32_16x16x32_bf16 v[32:35], v[152:155], v[210:213], v[32:35]
	v_mfma_f32_16x16x32_bf16 v[24:27], v[160:163], v[210:213], v[24:27]
	v_mfma_f32_16x16x32_bf16 v[16:19], v[152:155], v[218:221], v[16:19]
	v_mfma_f32_16x16x32_bf16 v[8:11], v[160:163], v[218:221], v[8:11]
	v_mfma_f32_16x16x32_bf16 v[60:63], v[164:167], v[180:183], v[60:63]
	v_mfma_f32_16x16x32_bf16 v[52:55], v[172:175], v[180:183], v[52:55]
	v_mfma_f32_16x16x32_bf16 v[44:47], v[164:167], v[188:191], v[44:47]
	v_mfma_f32_16x16x32_bf16 v[36:39], v[172:175], v[188:191], v[36:39]
	v_mfma_f32_16x16x32_bf16 v[28:31], v[164:167], v[206:209], v[28:31]
	v_mfma_f32_16x16x32_bf16 v[20:23], v[172:175], v[206:209], v[20:23]
	v_mfma_f32_16x16x32_bf16 v[12:15], v[164:167], v[214:217], v[12:15]
	v_mfma_f32_16x16x32_bf16 v[4:7], v[172:175], v[214:217], v[4:7]
	v_mfma_f32_16x16x32_bf16 v[60:63], v[168:171], v[184:187], v[60:63]
	v_mfma_f32_16x16x32_bf16 v[52:55], v[176:179], v[184:187], v[52:55]
	v_mfma_f32_16x16x32_bf16 v[44:47], v[168:171], v[192:195], v[44:47]
	v_mfma_f32_16x16x32_bf16 v[36:39], v[176:179], v[192:195], v[36:39]
	v_mfma_f32_16x16x32_bf16 v[28:31], v[168:171], v[210:213], v[28:31]
	v_mfma_f32_16x16x32_bf16 v[20:23], v[176:179], v[210:213], v[20:23]
	v_mfma_f32_16x16x32_bf16 v[12:15], v[168:171], v[218:221], v[12:15]
	v_mfma_f32_16x16x32_bf16 v[4:7], v[176:179], v[218:221], v[4:7]
	s_barrier
	s_add_i32 s62, s62, 2
	s_add_u32 s28, s28, 0x100
	s_addc_u32 s29, s29, 0
	s_add_u32 s60, s60, 0x100
	s_addc_u32 s61, s61, 0
	s_cmp_gt_u32 s62, 13

.LBB0_339:
	s_ashr_i32 s53, s52, 31
	v_cmp_lt_i64_e32 vcc, s[14:15], v[196:197]
	s_lshl_b64 s[14:15], s[52:53], 19
	s_add_u32 s14, s46, s14
	s_addc_u32 s15, s47, s15
	s_and_b64 s[16:17], vcc, exec
	s_cselect_b32 s43, s15, s19
	s_cselect_b32 s53, s14, s18
	s_ashr_i32 s51, s50, 31
	s_lshl_b64 s[16:17], s[50:51], 19
	s_add_u32 s16, s44, s16
	s_addc_u32 s17, s45, s17
	s_and_b64 s[22:23], vcc, exec
	s_cselect_b32 s51, s17, s21
	s_cselect_b32 s56, s16, s20
	s_add_u32 s18, s18, 0x40080
	s_addc_u32 s19, s19, 0
	s_add_u32 s57, s20, 0x100
	s_addc_u32 s58, s21, 0
	s_mov_b32 s59, -2
.Lk6_peel:
	s_add_u32 s20, s18, 0xfffc0080
	s_addc_u32 s21, s19, -1
	s_add_i32 s60, 0, 0x10000
	s_cmp_eq_u32 s59, 12
	s_cselect_b32 s23, s43, s21
	s_cselect_b32 s22, s53, s20
	s_cselect_b32 s21, s51, s58
	s_cselect_b32 s20, s56, s57
	s_add_i32 s62, 0, 0x14000
	v_add_u32_e32 v136, s60, v183
	v_add_u32_e32 v170, s62, v183
	ds_read_b128 v[108:111], v136
	ds_read_b128 v[112:115], v136 offset:1024
	ds_read_b128 v[132:135], v136 offset:2048
	ds_read_b128 v[136:139], v136 offset:3072
	ds_read_b128 v[140:143], v170
	ds_read_b128 v[144:147], v170 offset:1024
	ds_read_b128 v[166:169], v170 offset:2048
	ds_read_b128 v[170:173], v170 offset:3072
	v_lshl_add_u64 v[194:195], s[18:19], 0, v[162:163]
	s_add_i32 m0, s26, 0xc000
	ds_read_b128 v[174:177], v184
	ds_read_b128 v[178:181], v184 offset:1024
	ds_read_b128 v[186:189], v184 offset:2048
	ds_read_b128 v[190:193], v184 offset:3072
	ds_read_b128 v[206:209], v184 offset:4096
	ds_read_b128 v[210:213], v184 offset:5120
	ds_read_b128 v[214:217], v184 offset:6144
	ds_read_b128 v[218:221], v184 offset:7168
	global_load_lds_dwordx4 v[194:195], off
	v_lshl_add_u64 v[194:195], s[18:19], 0, v[164:165]
	s_add_i32 m0, s26, 0xe000
	s_nop 0
	global_load_lds_dwordx4 v[194:195], off
	s_waitcnt vmcnt(8)
	s_waitcnt lgkmcnt(0)
	s_barrier
	s_waitcnt lgkmcnt(0)
	v_mfma_f32_16x16x32_bf16 v[152:155], v[108:111], v[174:177], 0
	v_mfma_f32_16x16x32_bf16 v[148:151], v[132:135], v[174:177], 0
	v_mfma_f32_16x16x32_bf16 v[128:131], v[108:111], v[186:189], 0
	v_mfma_f32_16x16x32_bf16 v[124:127], v[132:135], v[186:189], 0
	v_mfma_f32_16x16x32_bf16 v[96:99], v[108:111], v[206:209], 0
	v_mfma_f32_16x16x32_bf16 v[92:95], v[132:135], v[206:209], 0
	v_mfma_f32_16x16x32_bf16 v[80:83], v[108:111], v[214:217], 0
	v_mfma_f32_16x16x32_bf16 v[76:79], v[132:135], v[214:217], 0
	v_mfma_f32_16x16x32_bf16 v[152:155], v[112:115], v[178:181], v[152:155]
	v_mfma_f32_16x16x32_bf16 v[148:151], v[136:139], v[178:181], v[148:151]
	v_mfma_f32_16x16x32_bf16 v[128:131], v[112:115], v[190:193], v[128:131]
	v_mfma_f32_16x16x32_bf16 v[124:127], v[136:139], v[190:193], v[124:127]
	v_mfma_f32_16x16x32_bf16 v[96:99], v[112:115], v[210:213], v[96:99]
	v_mfma_f32_16x16x32_bf16 v[92:95], v[136:139], v[210:213], v[92:95]
	v_mfma_f32_16x16x32_bf16 v[80:83], v[112:115], v[218:221], v[80:83]
	v_mfma_f32_16x16x32_bf16 v[76:79], v[136:139], v[218:221], v[76:79]
	v_mfma_f32_16x16x32_bf16 v[104:107], v[140:143], v[174:177], 0
	v_mfma_f32_16x16x32_bf16 v[100:103], v[166:169], v[174:177], 0
	v_mfma_f32_16x16x32_bf16 v[120:123], v[140:143], v[186:189], 0
	v_mfma_f32_16x16x32_bf16 v[116:119], v[166:169], v[186:189], 0
	v_mfma_f32_16x16x32_bf16 v[88:91], v[140:143], v[206:209], 0
	v_mfma_f32_16x16x32_bf16 v[84:87], v[166:169], v[206:209], 0
	v_mfma_f32_16x16x32_bf16 v[72:75], v[140:143], v[214:217], 0
	v_mfma_f32_16x16x32_bf16 v[68:71], v[166:169], v[214:217], 0
	v_mfma_f32_16x16x32_bf16 v[104:107], v[144:147], v[178:181], v[104:107]
	v_mfma_f32_16x16x32_bf16 v[100:103], v[170:173], v[178:181], v[100:103]
	v_mfma_f32_16x16x32_bf16 v[120:123], v[144:147], v[190:193], v[120:123]
	v_mfma_f32_16x16x32_bf16 v[116:119], v[170:173], v[190:193], v[116:119]
	v_mfma_f32_16x16x32_bf16 v[88:91], v[144:147], v[210:213], v[88:91]
	v_mfma_f32_16x16x32_bf16 v[84:87], v[170:173], v[210:213], v[84:87]
	v_mfma_f32_16x16x32_bf16 v[72:75], v[144:147], v[218:221], v[72:75]
	v_mfma_f32_16x16x32_bf16 v[68:71], v[170:173], v[218:221], v[68:71]
	s_barrier
	s_add_i32 s60, s60, s25
	v_lshl_add_u64 v[194:195], s[20:21], 0, v[2:3]
	s_mov_b32 m0, s60
	ds_read_b128 v[174:177], v184 offset:16384
	ds_read_b128 v[178:181], v184 offset:17408
	ds_read_b128 v[186:189], v184 offset:18432
	ds_read_b128 v[190:193], v184 offset:19456
	ds_read_b128 v[206:209], v184 offset:20480
	ds_read_b128 v[210:213], v184 offset:21504
	ds_read_b128 v[214:217], v184 offset:22528
	ds_read_b128 v[218:221], v184 offset:23552
	global_load_lds_dwordx4 v[194:195], off
	s_add_i32 m0, s60, 0x2000
	s_add_u32 s60, s20, 0x40000
	v_lshl_add_u64 v[236:237], s[20:21], 0, v[156:157]
	s_addc_u32 s61, s21, 0
	s_add_i32 s62, s62, s25
	global_load_lds_dwordx4 v[236:237], off
	v_lshl_add_u64 v[238:239], s[60:61], 0, v[2:3]
	s_mov_b32 m0, s62
	v_lshl_add_u64 v[240:241], s[22:23], 0, v[158:159]
	global_load_lds_dwordx4 v[238:239], off
	v_lshl_add_u64 v[238:239], s[60:61], 0, v[156:157]
	s_add_i32 m0, s62, 0x2000
	s_nop 0
	global_load_lds_dwordx4 v[238:239], off
	v_lshl_add_u64 v[238:239], s[22:23], 0, v[160:161]
	s_mov_b32 m0, s26
	s_nop 0
	global_load_lds_dwordx4 v[238:239], off
	s_mov_b32 m0, s27
	s_nop 0
	global_load_lds_dwordx4 v[240:241], off
	s_waitcnt vmcnt(8)
	s_waitcnt lgkmcnt(0)
	s_barrier
	s_waitcnt lgkmcnt(0)
	v_mfma_f32_16x16x32_bf16 v[64:67], v[108:111], v[174:177], 0
	v_mfma_f32_16x16x32_bf16 v[60:63], v[132:135], v[174:177], 0
	v_mfma_f32_16x16x32_bf16 v[48:51], v[108:111], v[186:189], 0
	v_mfma_f32_16x16x32_bf16 v[44:47], v[132:135], v[186:189], 0
	v_mfma_f32_16x16x32_bf16 v[32:35], v[108:111], v[206:209], 0
	v_mfma_f32_16x16x32_bf16 v[28:31], v[132:135], v[206:209], 0
	v_mfma_f32_16x16x32_bf16 v[16:19], v[108:111], v[214:217], 0
	v_mfma_f32_16x16x32_bf16 v[12:15], v[132:135], v[214:217], 0
	v_mfma_f32_16x16x32_bf16 v[64:67], v[112:115], v[178:181], v[64:67]
	v_mfma_f32_16x16x32_bf16 v[60:63], v[136:139], v[178:181], v[60:63]
	v_mfma_f32_16x16x32_bf16 v[48:51], v[112:115], v[190:193], v[48:51]
	v_mfma_f32_16x16x32_bf16 v[44:47], v[136:139], v[190:193], v[44:47]
	v_mfma_f32_16x16x32_bf16 v[32:35], v[112:115], v[210:213], v[32:35]
	v_mfma_f32_16x16x32_bf16 v[28:31], v[136:139], v[210:213], v[28:31]
	v_mfma_f32_16x16x32_bf16 v[16:19], v[112:115], v[218:221], v[16:19]
	v_mfma_f32_16x16x32_bf16 v[12:15], v[136:139], v[218:221], v[12:15]
	v_mfma_f32_16x16x32_bf16 v[56:59], v[140:143], v[174:177], 0
	v_mfma_f32_16x16x32_bf16 v[52:55], v[166:169], v[174:177], 0
	v_mfma_f32_16x16x32_bf16 v[40:43], v[140:143], v[186:189], 0
	v_mfma_f32_16x16x32_bf16 v[36:39], v[166:169], v[186:189], 0
	v_mfma_f32_16x16x32_bf16 v[24:27], v[140:143], v[206:209], 0
	v_mfma_f32_16x16x32_bf16 v[20:23], v[166:169], v[206:209], 0
	v_mfma_f32_16x16x32_bf16 v[8:11], v[140:143], v[214:217], 0
	v_mfma_f32_16x16x32_bf16 v[4:7], v[166:169], v[214:217], 0
	v_mfma_f32_16x16x32_bf16 v[56:59], v[144:147], v[178:181], v[56:59]
	v_mfma_f32_16x16x32_bf16 v[52:55], v[170:173], v[178:181], v[52:55]
	v_mfma_f32_16x16x32_bf16 v[40:43], v[144:147], v[190:193], v[40:43]
	v_mfma_f32_16x16x32_bf16 v[36:39], v[170:173], v[190:193], v[36:39]
	v_mfma_f32_16x16x32_bf16 v[24:27], v[144:147], v[210:213], v[24:27]
	v_mfma_f32_16x16x32_bf16 v[20:23], v[170:173], v[210:213], v[20:23]
	v_mfma_f32_16x16x32_bf16 v[8:11], v[144:147], v[218:221], v[8:11]
	v_mfma_f32_16x16x32_bf16 v[4:7], v[170:173], v[218:221], v[4:7]
	s_barrier
	s_add_i32 s60, 0, 0x18000
	s_add_i32 s61, 0, 0x1c000
	v_add_u32_e32 v136, s60, v183
	v_add_u32_e32 v170, s61, v183
	ds_read_b128 v[108:111], v136
	ds_read_b128 v[112:115], v136 offset:1024
	ds_read_b128 v[132:135], v136 offset:2048
	ds_read_b128 v[136:139], v136 offset:3072
	ds_read_b128 v[140:143], v170
	ds_read_b128 v[144:147], v170 offset:1024
	ds_read_b128 v[166:169], v170 offset:2048
	ds_read_b128 v[170:173], v170 offset:3072
	s_add_u32 s22, s22, 0x40000
	s_addc_u32 s23, s23, 0
	s_mov_b32 m0, s28
	v_lshl_add_u64 v[242:243], s[22:23], 0, v[160:161]
	ds_read_b128 v[174:177], v184 offset:32768
	ds_read_b128 v[178:181], v184 offset:33792
	ds_read_b128 v[186:189], v184 offset:34816
	ds_read_b128 v[190:193], v184 offset:35840
	ds_read_b128 v[206:209], v184 offset:36864
	ds_read_b128 v[210:213], v184 offset:37888
	ds_read_b128 v[214:217], v184 offset:38912
	ds_read_b128 v[218:221], v184 offset:39936
	global_load_lds_dwordx4 v[242:243], off
	v_lshl_add_u64 v[242:243], s[22:23], 0, v[158:159]
	s_mov_b32 m0, s29
	s_nop 0
	global_load_lds_dwordx4 v[242:243], off
	s_waitcnt vmcnt(8)
	s_waitcnt lgkmcnt(0)
	s_barrier
	s_waitcnt lgkmcnt(0)
	v_mfma_f32_16x16x32_bf16 v[152:155], v[108:111], v[174:177], v[152:155]
	v_mfma_f32_16x16x32_bf16 v[148:151], v[132:135], v[174:177], v[148:151]
	v_mfma_f32_16x16x32_bf16 v[128:131], v[108:111], v[186:189], v[128:131]
	v_mfma_f32_16x16x32_bf16 v[124:127], v[132:135], v[186:189], v[124:127]
	v_mfma_f32_16x16x32_bf16 v[96:99], v[108:111], v[206:209], v[96:99]
	v_mfma_f32_16x16x32_bf16 v[92:95], v[132:135], v[206:209], v[92:95]
	v_mfma_f32_16x16x32_bf16 v[80:83], v[108:111], v[214:217], v[80:83]
	v_mfma_f32_16x16x32_bf16 v[76:79], v[132:135], v[214:217], v[76:79]
	v_mfma_f32_16x16x32_bf16 v[152:155], v[112:115], v[178:181], v[152:155]
	v_mfma_f32_16x16x32_bf16 v[148:151], v[136:139], v[178:181], v[148:151]
	v_mfma_f32_16x16x32_bf16 v[128:131], v[112:115], v[190:193], v[128:131]
	v_mfma_f32_16x16x32_bf16 v[124:127], v[136:139], v[190:193], v[124:127]
	v_mfma_f32_16x16x32_bf16 v[96:99], v[112:115], v[210:213], v[96:99]
	v_mfma_f32_16x16x32_bf16 v[92:95], v[136:139], v[210:213], v[92:95]
	v_mfma_f32_16x16x32_bf16 v[80:83], v[112:115], v[218:221], v[80:83]
	v_mfma_f32_16x16x32_bf16 v[76:79], v[136:139], v[218:221], v[76:79]
	v_mfma_f32_16x16x32_bf16 v[104:107], v[140:143], v[174:177], v[104:107]
	v_mfma_f32_16x16x32_bf16 v[100:103], v[166:169], v[174:177], v[100:103]
	v_mfma_f32_16x16x32_bf16 v[120:123], v[140:143], v[186:189], v[120:123]
	v_mfma_f32_16x16x32_bf16 v[116:119], v[166:169], v[186:189], v[116:119]
	v_mfma_f32_16x16x32_bf16 v[88:91], v[140:143], v[206:209], v[88:91]
	v_mfma_f32_16x16x32_bf16 v[84:87], v[166:169], v[206:209], v[84:87]
	v_mfma_f32_16x16x32_bf16 v[72:75], v[140:143], v[214:217], v[72:75]
	v_mfma_f32_16x16x32_bf16 v[68:71], v[166:169], v[214:217], v[68:71]
	v_mfma_f32_16x16x32_bf16 v[104:107], v[144:147], v[178:181], v[104:107]
	v_mfma_f32_16x16x32_bf16 v[100:103], v[170:173], v[178:181], v[100:103]
	v_mfma_f32_16x16x32_bf16 v[120:123], v[144:147], v[190:193], v[120:123]
	v_mfma_f32_16x16x32_bf16 v[116:119], v[170:173], v[190:193], v[116:119]
	v_mfma_f32_16x16x32_bf16 v[88:91], v[144:147], v[210:213], v[88:91]
	v_mfma_f32_16x16x32_bf16 v[84:87], v[170:173], v[210:213], v[84:87]
	v_mfma_f32_16x16x32_bf16 v[72:75], v[144:147], v[218:221], v[72:75]
	v_mfma_f32_16x16x32_bf16 v[68:71], v[170:173], v[218:221], v[68:71]
	s_barrier
	s_add_i32 s22, s60, s25
	v_lshl_add_u64 v[194:195], v[194:195], 0, s[96:97]
	s_mov_b32 m0, s22
	ds_read_b128 v[174:177], v184 offset:49152
	ds_read_b128 v[178:181], v184 offset:50176
	ds_read_b128 v[186:189], v184 offset:51200
	ds_read_b128 v[190:193], v184 offset:52224
	ds_read_b128 v[206:209], v184 offset:53248
	ds_read_b128 v[210:213], v184 offset:54272
	ds_read_b128 v[214:217], v184 offset:55296
	ds_read_b128 v[218:221], v184 offset:56320
	global_load_lds_dwordx4 v[194:195], off
	s_add_i32 m0, s22, 0x2000
	s_add_u32 s20, s20, 0x40080
	v_lshl_add_u64 v[194:195], v[236:237], 0, s[96:97]
	s_addc_u32 s21, s21, 0
	s_add_i32 s22, s61, s25
	global_load_lds_dwordx4 v[194:195], off
	v_lshl_add_u64 v[194:195], s[20:21], 0, v[2:3]
	s_mov_b32 m0, s22
	s_nop 0
	global_load_lds_dwordx4 v[194:195], off
	v_lshl_add_u64 v[194:195], s[20:21], 0, v[156:157]
	s_add_i32 m0, s22, 0x2000
	s_nop 0
	global_load_lds_dwordx4 v[194:195], off
	v_lshl_add_u64 v[194:195], v[238:239], 0, s[96:97]
	s_mov_b32 m0, s34
	s_nop 0
	global_load_lds_dwordx4 v[194:195], off
	v_lshl_add_u64 v[194:195], v[240:241], 0, s[96:97]
	s_mov_b32 m0, s35
	s_nop 0
	global_load_lds_dwordx4 v[194:195], off
	s_waitcnt vmcnt(8)
	s_waitcnt lgkmcnt(0)
	s_barrier
	s_waitcnt lgkmcnt(0)
	v_mfma_f32_16x16x32_bf16 v[64:67], v[108:111], v[174:177], v[64:67]
	v_mfma_f32_16x16x32_bf16 v[60:63], v[132:135], v[174:177], v[60:63]
	v_mfma_f32_16x16x32_bf16 v[48:51], v[108:111], v[186:189], v[48:51]
	v_mfma_f32_16x16x32_bf16 v[44:47], v[132:135], v[186:189], v[44:47]
	v_mfma_f32_16x16x32_bf16 v[32:35], v[108:111], v[206:209], v[32:35]
	v_mfma_f32_16x16x32_bf16 v[28:31], v[132:135], v[206:209], v[28:31]
	v_mfma_f32_16x16x32_bf16 v[16:19], v[108:111], v[214:217], v[16:19]
	v_mfma_f32_16x16x32_bf16 v[12:15], v[132:135], v[214:217], v[12:15]
	v_mfma_f32_16x16x32_bf16 v[64:67], v[112:115], v[178:181], v[64:67]
	v_mfma_f32_16x16x32_bf16 v[60:63], v[136:139], v[178:181], v[60:63]
	v_mfma_f32_16x16x32_bf16 v[48:51], v[112:115], v[190:193], v[48:51]
	v_mfma_f32_16x16x32_bf16 v[44:47], v[136:139], v[190:193], v[44:47]
	v_mfma_f32_16x16x32_bf16 v[32:35], v[112:115], v[210:213], v[32:35]
	v_mfma_f32_16x16x32_bf16 v[28:31], v[136:139], v[210:213], v[28:31]
	v_mfma_f32_16x16x32_bf16 v[16:19], v[112:115], v[218:221], v[16:19]
	v_mfma_f32_16x16x32_bf16 v[12:15], v[136:139], v[218:221], v[12:15]
	v_mfma_f32_16x16x32_bf16 v[56:59], v[140:143], v[174:177], v[56:59]
	v_mfma_f32_16x16x32_bf16 v[52:55], v[166:169], v[174:177], v[52:55]
	v_mfma_f32_16x16x32_bf16 v[40:43], v[140:143], v[186:189], v[40:43]
	v_mfma_f32_16x16x32_bf16 v[36:39], v[166:169], v[186:189], v[36:39]
	v_mfma_f32_16x16x32_bf16 v[24:27], v[140:143], v[206:209], v[24:27]
	v_mfma_f32_16x16x32_bf16 v[20:23], v[166:169], v[206:209], v[20:23]
	v_mfma_f32_16x16x32_bf16 v[8:11], v[140:143], v[214:217], v[8:11]
	v_mfma_f32_16x16x32_bf16 v[4:7], v[166:169], v[214:217], v[4:7]
	v_mfma_f32_16x16x32_bf16 v[56:59], v[144:147], v[178:181], v[56:59]
	v_mfma_f32_16x16x32_bf16 v[52:55], v[170:173], v[178:181], v[52:55]
	v_mfma_f32_16x16x32_bf16 v[40:43], v[144:147], v[190:193], v[40:43]
	v_mfma_f32_16x16x32_bf16 v[36:39], v[170:173], v[190:193], v[36:39]
	v_mfma_f32_16x16x32_bf16 v[24:27], v[144:147], v[210:213], v[24:27]
	v_mfma_f32_16x16x32_bf16 v[20:23], v[170:173], v[210:213], v[20:23]
	v_mfma_f32_16x16x32_bf16 v[8:11], v[144:147], v[218:221], v[8:11]
	v_mfma_f32_16x16x32_bf16 v[4:7], v[170:173], v[218:221], v[4:7]
	s_barrier
	s_add_i32 s59, s59, 2
	s_add_u32 s18, s18, 0x100
	s_addc_u32 s19, s19, 0
	s_add_u32 s57, s57, 0x100
	s_addc_u32 s58, s58, 0
	s_cmp_gt_u32 s59, 13

.LBB0_751:
	v_lshlrev_b32_e32 v2, 4, v0
	s_lshl_b32 s100, s16, 14
	s_add_u32 s100, s50, s100
	s_addc_u32 s101, s51, 0
	v_readfirstlane_b32 s57, v2
	s_nop 3
	s_add_i32 m0, s57, 0x20400
	s_nop 0
	global_load_lds_dwordx4 v2, s[100:101]
	v_add_u32_e32 v2, 0x2000, v2
	s_add_i32 m0, s57, 0x22400
	s_nop 0
	global_load_lds_dwordx4 v2, s[100:101]
	s_ashr_i32 s57, s56, 31
	s_lshl_b64 s[22:23], s[56:57], 19
	s_add_u32 s58, s28, s22
	s_addc_u32 s59, s29, s23
	s_and_b64 s[22:23], s[38:39], exec
	s_cselect_b32 s15, s59, s19
	s_cselect_b32 s17, s58, s18
	s_ashr_i32 s55, s54, 31
	s_lshl_b64 s[22:23], s[54:55], 19
	s_add_u32 s60, s30, s22
	s_addc_u32 s61, s31, s23
	s_and_b64 s[22:23], s[38:39], exec
	s_cselect_b32 s24, s61, s21
	s_cselect_b32 s25, s60, s20
	s_add_u32 s18, s18, 0x40080
	s_addc_u32 s19, s19, 0
	s_add_u32 s26, s20, 0x100
	s_addc_u32 s27, s21, 0
	s_mov_b32 s40, -2
	s_waitcnt lgkmcnt(0)
.Lk1_peel:
	s_add_u32 s20, s18, 0xfffc0080
	s_addc_u32 s21, s19, -1
	s_add_i32 s41, 0, 0x10000
	s_cmp_eq_u32 s40, 12
	s_cselect_b32 s23, s15, s21
	s_cselect_b32 s22, s17, s20
	v_add_u32_e32 v2, s41, v157
	s_cselect_b32 s21, s24, s27
	s_cselect_b32 s20, s25, s26
	s_add_i32 s55, 0, 0x14000
	ds_read_b128 v[144:147], v2
	ds_read_b128 v[148:151], v2 offset:1024
	ds_read_b128 v[152:155], v2 offset:2048
	ds_read_b128 v[160:163], v2 offset:3072
	v_add_u32_e32 v2, s55, v157
	ds_read_b128 v[164:167], v2
	ds_read_b128 v[168:171], v2 offset:1024
	ds_read_b128 v[172:175], v2 offset:2048
	ds_read_b128 v[176:179], v2 offset:3072
	v_lshl_add_u64 v[234:235], s[18:19], 0, v[140:141]
	s_add_i32 m0, s36, 0xc000
	ds_read_b128 v[180:183], v158
	ds_read_b128 v[184:187], v158 offset:1024
	ds_read_b128 v[188:191], v158 offset:2048
	ds_read_b128 v[192:195], v158 offset:3072
	ds_read_b128 v[206:209], v158 offset:4096
	ds_read_b128 v[210:213], v158 offset:5120
	ds_read_b128 v[214:217], v158 offset:6144
	ds_read_b128 v[218:221], v158 offset:7168
	global_load_lds_dwordx4 v[234:235], off
	v_lshl_add_u64 v[234:235], s[18:19], 0, v[142:143]
	s_add_i32 m0, s36, 0xe000
	s_nop 0
	global_load_lds_dwordx4 v[234:235], off
	s_waitcnt vmcnt(8)
	s_waitcnt lgkmcnt(0)
	s_barrier
	s_waitcnt lgkmcnt(0)
	v_mfma_f32_16x16x32_bf16 v[120:123], v[144:147], v[180:183], 0
	v_mfma_f32_16x16x32_bf16 v[116:119], v[152:155], v[180:183], 0
	v_mfma_f32_16x16x32_bf16 v[104:107], v[144:147], v[188:191], 0
	v_mfma_f32_16x16x32_bf16 v[100:103], v[152:155], v[188:191], 0
	v_mfma_f32_16x16x32_bf16 v[88:91], v[144:147], v[206:209], 0
	v_mfma_f32_16x16x32_bf16 v[84:87], v[152:155], v[206:209], 0
	v_mfma_f32_16x16x32_bf16 v[72:75], v[144:147], v[214:217], 0
	v_mfma_f32_16x16x32_bf16 v[68:71], v[152:155], v[214:217], 0
	v_mfma_f32_16x16x32_bf16 v[120:123], v[148:151], v[184:187], v[120:123]
	v_mfma_f32_16x16x32_bf16 v[116:119], v[160:163], v[184:187], v[116:119]
	v_mfma_f32_16x16x32_bf16 v[104:107], v[148:151], v[192:195], v[104:107]
	v_mfma_f32_16x16x32_bf16 v[100:103], v[160:163], v[192:195], v[100:103]
	v_mfma_f32_16x16x32_bf16 v[88:91], v[148:151], v[210:213], v[88:91]
	v_mfma_f32_16x16x32_bf16 v[84:87], v[160:163], v[210:213], v[84:87]
	v_mfma_f32_16x16x32_bf16 v[72:75], v[148:151], v[218:221], v[72:75]
	v_mfma_f32_16x16x32_bf16 v[68:71], v[160:163], v[218:221], v[68:71]
	v_mfma_f32_16x16x32_bf16 v[128:131], v[164:167], v[180:183], 0
	v_mfma_f32_16x16x32_bf16 v[124:127], v[172:175], v[180:183], 0
	v_mfma_f32_16x16x32_bf16 v[112:115], v[164:167], v[188:191], 0
	v_mfma_f32_16x16x32_bf16 v[108:111], v[172:175], v[188:191], 0
	v_mfma_f32_16x16x32_bf16 v[96:99], v[164:167], v[206:209], 0
	v_mfma_f32_16x16x32_bf16 v[92:95], v[172:175], v[206:209], 0
	v_mfma_f32_16x16x32_bf16 v[80:83], v[164:167], v[214:217], 0
	v_mfma_f32_16x16x32_bf16 v[76:79], v[172:175], v[214:217], 0
	v_mfma_f32_16x16x32_bf16 v[128:131], v[168:171], v[184:187], v[128:131]
	v_mfma_f32_16x16x32_bf16 v[124:127], v[176:179], v[184:187], v[124:127]
	v_mfma_f32_16x16x32_bf16 v[112:115], v[168:171], v[192:195], v[112:115]
	v_mfma_f32_16x16x32_bf16 v[108:111], v[176:179], v[192:195], v[108:111]
	v_mfma_f32_16x16x32_bf16 v[96:99], v[168:171], v[210:213], v[96:99]
	v_mfma_f32_16x16x32_bf16 v[92:95], v[176:179], v[210:213], v[92:95]
	v_mfma_f32_16x16x32_bf16 v[80:83], v[168:171], v[218:221], v[80:83]
	v_mfma_f32_16x16x32_bf16 v[76:79], v[176:179], v[218:221], v[76:79]
	s_barrier
	s_add_i32 s41, s41, s35
	v_lshl_add_u64 v[234:235], s[20:21], 0, v[134:135]
	s_mov_b32 m0, s41
	ds_read_b128 v[180:183], v158 offset:16384
	ds_read_b128 v[184:187], v158 offset:17408
	ds_read_b128 v[188:191], v158 offset:18432
	ds_read_b128 v[192:195], v158 offset:19456
	ds_read_b128 v[206:209], v158 offset:20480
	ds_read_b128 v[210:213], v158 offset:21504
	ds_read_b128 v[214:217], v158 offset:22528
	ds_read_b128 v[218:221], v158 offset:23552
	global_load_lds_dwordx4 v[234:235], off
	s_add_i32 m0, s41, 0x2000
	s_add_u32 s42, s20, 0x40000
	v_lshl_add_u64 v[236:237], s[20:21], 0, v[138:139]
	s_addc_u32 s43, s21, 0
	s_add_i32 s41, s55, s35
	global_load_lds_dwordx4 v[236:237], off
	v_lshl_add_u64 v[238:239], s[42:43], 0, v[134:135]
	s_mov_b32 m0, s41
	v_lshl_add_u64 v[240:241], s[22:23], 0, v[136:137]
	global_load_lds_dwordx4 v[238:239], off
	v_lshl_add_u64 v[238:239], s[42:43], 0, v[138:139]
	s_add_i32 m0, s41, 0x2000
	s_nop 0
	global_load_lds_dwordx4 v[238:239], off
	v_lshl_add_u64 v[238:239], s[22:23], 0, v[132:133]
	s_mov_b32 m0, s36
	s_nop 0
	global_load_lds_dwordx4 v[238:239], off
	s_mov_b32 m0, s37
	s_nop 0
	global_load_lds_dwordx4 v[240:241], off
	s_waitcnt vmcnt(8)
	s_waitcnt lgkmcnt(0)
	s_barrier
	s_waitcnt lgkmcnt(0)
	v_mfma_f32_16x16x32_bf16 v[56:59], v[144:147], v[180:183], 0
	v_mfma_f32_16x16x32_bf16 v[52:55], v[152:155], v[180:183], 0
	v_mfma_f32_16x16x32_bf16 v[40:43], v[144:147], v[188:191], 0
	v_mfma_f32_16x16x32_bf16 v[36:39], v[152:155], v[188:191], 0
	v_mfma_f32_16x16x32_bf16 v[24:27], v[144:147], v[206:209], 0
	v_mfma_f32_16x16x32_bf16 v[20:23], v[152:155], v[206:209], 0
	v_mfma_f32_16x16x32_bf16 v[8:11], v[144:147], v[214:217], 0
	v_mfma_f32_16x16x32_bf16 v[4:7], v[152:155], v[214:217], 0
	v_mfma_f32_16x16x32_bf16 v[56:59], v[148:151], v[184:187], v[56:59]
	v_mfma_f32_16x16x32_bf16 v[52:55], v[160:163], v[184:187], v[52:55]
	v_mfma_f32_16x16x32_bf16 v[40:43], v[148:151], v[192:195], v[40:43]
	v_mfma_f32_16x16x32_bf16 v[36:39], v[160:163], v[192:195], v[36:39]
	v_mfma_f32_16x16x32_bf16 v[24:27], v[148:151], v[210:213], v[24:27]
	v_mfma_f32_16x16x32_bf16 v[20:23], v[160:163], v[210:213], v[20:23]
	v_mfma_f32_16x16x32_bf16 v[8:11], v[148:151], v[218:221], v[8:11]
	v_mfma_f32_16x16x32_bf16 v[4:7], v[160:163], v[218:221], v[4:7]
	v_mfma_f32_16x16x32_bf16 v[64:67], v[164:167], v[180:183], 0
	v_mfma_f32_16x16x32_bf16 v[60:63], v[172:175], v[180:183], 0
	v_mfma_f32_16x16x32_bf16 v[48:51], v[164:167], v[188:191], 0
	v_mfma_f32_16x16x32_bf16 v[44:47], v[172:175], v[188:191], 0
	v_mfma_f32_16x16x32_bf16 v[32:35], v[164:167], v[206:209], 0
	v_mfma_f32_16x16x32_bf16 v[28:31], v[172:175], v[206:209], 0
	v_mfma_f32_16x16x32_bf16 v[16:19], v[164:167], v[214:217], 0
	v_mfma_f32_16x16x32_bf16 v[12:15], v[172:175], v[214:217], 0
	v_mfma_f32_16x16x32_bf16 v[64:67], v[168:171], v[184:187], v[64:67]
	v_mfma_f32_16x16x32_bf16 v[60:63], v[176:179], v[184:187], v[60:63]
	v_mfma_f32_16x16x32_bf16 v[48:51], v[168:171], v[192:195], v[48:51]
	v_mfma_f32_16x16x32_bf16 v[44:47], v[176:179], v[192:195], v[44:47]
	v_mfma_f32_16x16x32_bf16 v[32:35], v[168:171], v[210:213], v[32:35]
	v_mfma_f32_16x16x32_bf16 v[28:31], v[176:179], v[210:213], v[28:31]
	v_mfma_f32_16x16x32_bf16 v[16:19], v[168:171], v[218:221], v[16:19]
	v_mfma_f32_16x16x32_bf16 v[12:15], v[176:179], v[218:221], v[12:15]
	s_barrier
	s_add_i32 s41, 0, 0x18000
	v_add_u32_e32 v2, s41, v157
	s_add_i32 s42, 0, 0x1c000
	ds_read_b128 v[144:147], v2
	ds_read_b128 v[148:151], v2 offset:1024
	ds_read_b128 v[152:155], v2 offset:2048
	ds_read_b128 v[160:163], v2 offset:3072
	v_add_u32_e32 v2, s42, v157
	ds_read_b128 v[164:167], v2
	ds_read_b128 v[168:171], v2 offset:1024
	ds_read_b128 v[172:175], v2 offset:2048
	ds_read_b128 v[176:179], v2 offset:3072
	s_add_u32 s22, s22, 0x40000
	s_addc_u32 s23, s23, 0
	s_mov_b32 m0, s64
	v_lshl_add_u64 v[242:243], s[22:23], 0, v[132:133]
	ds_read_b128 v[180:183], v158 offset:32768
	ds_read_b128 v[184:187], v158 offset:33792
	ds_read_b128 v[188:191], v158 offset:34816
	ds_read_b128 v[192:195], v158 offset:35840
	ds_read_b128 v[206:209], v158 offset:36864
	ds_read_b128 v[210:213], v158 offset:37888
	ds_read_b128 v[214:217], v158 offset:38912
	ds_read_b128 v[218:221], v158 offset:39936
	global_load_lds_dwordx4 v[242:243], off
	v_lshl_add_u64 v[242:243], s[22:23], 0, v[136:137]
	s_mov_b32 m0, s65
	s_nop 0
	global_load_lds_dwordx4 v[242:243], off
	s_waitcnt vmcnt(8)
	s_waitcnt lgkmcnt(0)
	s_barrier
	s_waitcnt lgkmcnt(0)
	v_mfma_f32_16x16x32_bf16 v[120:123], v[144:147], v[180:183], v[120:123]
	v_mfma_f32_16x16x32_bf16 v[116:119], v[152:155], v[180:183], v[116:119]
	v_mfma_f32_16x16x32_bf16 v[104:107], v[144:147], v[188:191], v[104:107]
	v_mfma_f32_16x16x32_bf16 v[100:103], v[152:155], v[188:191], v[100:103]
	v_mfma_f32_16x16x32_bf16 v[88:91], v[144:147], v[206:209], v[88:91]
	v_mfma_f32_16x16x32_bf16 v[84:87], v[152:155], v[206:209], v[84:87]
	v_mfma_f32_16x16x32_bf16 v[72:75], v[144:147], v[214:217], v[72:75]
	v_mfma_f32_16x16x32_bf16 v[68:71], v[152:155], v[214:217], v[68:71]
	v_mfma_f32_16x16x32_bf16 v[120:123], v[148:151], v[184:187], v[120:123]
	v_mfma_f32_16x16x32_bf16 v[116:119], v[160:163], v[184:187], v[116:119]
	v_mfma_f32_16x16x32_bf16 v[104:107], v[148:151], v[192:195], v[104:107]
	v_mfma_f32_16x16x32_bf16 v[100:103], v[160:163], v[192:195], v[100:103]
	v_mfma_f32_16x16x32_bf16 v[88:91], v[148:151], v[210:213], v[88:91]
	v_mfma_f32_16x16x32_bf16 v[84:87], v[160:163], v[210:213], v[84:87]
	v_mfma_f32_16x16x32_bf16 v[72:75], v[148:151], v[218:221], v[72:75]
	v_mfma_f32_16x16x32_bf16 v[68:71], v[160:163], v[218:221], v[68:71]
	v_mfma_f32_16x16x32_bf16 v[128:131], v[164:167], v[180:183], v[128:131]
	v_mfma_f32_16x16x32_bf16 v[124:127], v[172:175], v[180:183], v[124:127]
	v_mfma_f32_16x16x32_bf16 v[112:115], v[164:167], v[188:191], v[112:115]
	v_mfma_f32_16x16x32_bf16 v[108:111], v[172:175], v[188:191], v[108:111]
	v_mfma_f32_16x16x32_bf16 v[96:99], v[164:167], v[206:209], v[96:99]
	v_mfma_f32_16x16x32_bf16 v[92:95], v[172:175], v[206:209], v[92:95]
	v_mfma_f32_16x16x32_bf16 v[80:83], v[164:167], v[214:217], v[80:83]
	v_mfma_f32_16x16x32_bf16 v[76:79], v[172:175], v[214:217], v[76:79]
	v_mfma_f32_16x16x32_bf16 v[128:131], v[168:171], v[184:187], v[128:131]
	v_mfma_f32_16x16x32_bf16 v[124:127], v[176:179], v[184:187], v[124:127]
	v_mfma_f32_16x16x32_bf16 v[112:115], v[168:171], v[192:195], v[112:115]
	v_mfma_f32_16x16x32_bf16 v[108:111], v[176:179], v[192:195], v[108:111]
	v_mfma_f32_16x16x32_bf16 v[96:99], v[168:171], v[210:213], v[96:99]
	v_mfma_f32_16x16x32_bf16 v[92:95], v[176:179], v[210:213], v[92:95]
	v_mfma_f32_16x16x32_bf16 v[80:83], v[168:171], v[218:221], v[80:83]
	v_mfma_f32_16x16x32_bf16 v[76:79], v[176:179], v[218:221], v[76:79]
	s_barrier
	s_add_i32 s22, s41, s35
	v_lshl_add_u64 v[234:235], v[234:235], 0, s[96:97]
	s_mov_b32 m0, s22
	ds_read_b128 v[180:183], v158 offset:49152
	ds_read_b128 v[184:187], v158 offset:50176
	ds_read_b128 v[188:191], v158 offset:51200
	ds_read_b128 v[192:195], v158 offset:52224
	ds_read_b128 v[206:209], v158 offset:53248
	ds_read_b128 v[210:213], v158 offset:54272
	ds_read_b128 v[214:217], v158 offset:55296
	ds_read_b128 v[218:221], v158 offset:56320
	global_load_lds_dwordx4 v[234:235], off
	s_add_i32 m0, s22, 0x2000
	s_add_u32 s20, s20, 0x40080
	v_lshl_add_u64 v[234:235], v[236:237], 0, s[96:97]
	s_addc_u32 s21, s21, 0
	s_add_i32 s22, s42, s35
	global_load_lds_dwordx4 v[234:235], off
	v_lshl_add_u64 v[234:235], s[20:21], 0, v[134:135]
	s_mov_b32 m0, s22
	s_nop 0
	global_load_lds_dwordx4 v[234:235], off
	v_lshl_add_u64 v[234:235], s[20:21], 0, v[138:139]
	s_add_i32 m0, s22, 0x2000
	s_nop 0
	global_load_lds_dwordx4 v[234:235], off
	v_lshl_add_u64 v[234:235], v[238:239], 0, s[96:97]
	s_mov_b32 m0, s67
	s_nop 0
	global_load_lds_dwordx4 v[234:235], off
	v_lshl_add_u64 v[234:235], v[240:241], 0, s[96:97]
	s_mov_b32 m0, s68
	s_nop 0
	global_load_lds_dwordx4 v[234:235], off
	s_waitcnt vmcnt(8)
	s_waitcnt lgkmcnt(0)
	s_barrier
	s_waitcnt lgkmcnt(0)
	v_mfma_f32_16x16x32_bf16 v[56:59], v[144:147], v[180:183], v[56:59]
	v_mfma_f32_16x16x32_bf16 v[52:55], v[152:155], v[180:183], v[52:55]
	v_mfma_f32_16x16x32_bf16 v[40:43], v[144:147], v[188:191], v[40:43]
	v_mfma_f32_16x16x32_bf16 v[36:39], v[152:155], v[188:191], v[36:39]
	v_mfma_f32_16x16x32_bf16 v[24:27], v[144:147], v[206:209], v[24:27]
	v_mfma_f32_16x16x32_bf16 v[20:23], v[152:155], v[206:209], v[20:23]
	v_mfma_f32_16x16x32_bf16 v[8:11], v[144:147], v[214:217], v[8:11]
	v_mfma_f32_16x16x32_bf16 v[4:7], v[152:155], v[214:217], v[4:7]
	v_mfma_f32_16x16x32_bf16 v[56:59], v[148:151], v[184:187], v[56:59]
	v_mfma_f32_16x16x32_bf16 v[52:55], v[160:163], v[184:187], v[52:55]
	v_mfma_f32_16x16x32_bf16 v[40:43], v[148:151], v[192:195], v[40:43]
	v_mfma_f32_16x16x32_bf16 v[36:39], v[160:163], v[192:195], v[36:39]
	v_mfma_f32_16x16x32_bf16 v[24:27], v[148:151], v[210:213], v[24:27]
	v_mfma_f32_16x16x32_bf16 v[20:23], v[160:163], v[210:213], v[20:23]
	v_mfma_f32_16x16x32_bf16 v[8:11], v[148:151], v[218:221], v[8:11]
	v_mfma_f32_16x16x32_bf16 v[4:7], v[160:163], v[218:221], v[4:7]
	v_mfma_f32_16x16x32_bf16 v[64:67], v[164:167], v[180:183], v[64:67]
	v_mfma_f32_16x16x32_bf16 v[60:63], v[172:175], v[180:183], v[60:63]
	v_mfma_f32_16x16x32_bf16 v[48:51], v[164:167], v[188:191], v[48:51]
	v_mfma_f32_16x16x32_bf16 v[44:47], v[172:175], v[188:191], v[44:47]
	v_mfma_f32_16x16x32_bf16 v[32:35], v[164:167], v[206:209], v[32:35]
	v_mfma_f32_16x16x32_bf16 v[28:31], v[172:175], v[206:209], v[28:31]
	v_mfma_f32_16x16x32_bf16 v[16:19], v[164:167], v[214:217], v[16:19]
	v_mfma_f32_16x16x32_bf16 v[12:15], v[172:175], v[214:217], v[12:15]
	v_mfma_f32_16x16x32_bf16 v[64:67], v[168:171], v[184:187], v[64:67]
	v_mfma_f32_16x16x32_bf16 v[60:63], v[176:179], v[184:187], v[60:63]
	v_mfma_f32_16x16x32_bf16 v[48:51], v[168:171], v[192:195], v[48:51]
	v_mfma_f32_16x16x32_bf16 v[44:47], v[176:179], v[192:195], v[44:47]
	v_mfma_f32_16x16x32_bf16 v[32:35], v[168:171], v[210:213], v[32:35]
	v_mfma_f32_16x16x32_bf16 v[28:31], v[176:179], v[210:213], v[28:31]
	v_mfma_f32_16x16x32_bf16 v[16:19], v[168:171], v[218:221], v[16:19]
	v_mfma_f32_16x16x32_bf16 v[12:15], v[176:179], v[218:221], v[12:15]
	s_barrier
	s_add_i32 s40, s40, 2
	s_add_u32 s18, s18, 0x100
	s_addc_u32 s19, s19, 0
	s_add_u32 s26, s26, 0x100
	s_addc_u32 s27, s27, 0
	s_cmp_gt_u32 s40, 13
